# attention: running max folded into the first QK MFMA's C operand (bias vector in v188-v203, 14 item invariants parked in spare LDS incl. 16 KiB extra static LDS); 32 v_sub per tile removed
# speedup vs baseline: 1.0069x; 1.0013x over previous
.LBB0_28:
	s_waitcnt vmcnt(21)
	v_lshlrev_b32_e32 v51, 16, v46
	v_and_b32_e32 v46, 0xffff0000, v46
	s_waitcnt vmcnt(6)
	v_mul_f32_e32 v51, v50, v51
	v_mul_f32_e32 v46, v50, v46
	v_cvt_pk_bf16_f32 v126, v51, v46
	v_lshlrev_b32_e32 v46, 16, v47
	v_and_b32_e32 v47, 0xffff0000, v47
	v_mul_f32_e32 v46, v50, v46
	v_mul_f32_e32 v47, v50, v47
	v_cvt_pk_bf16_f32 v127, v46, v47
	v_lshlrev_b32_e32 v46, 16, v48
	v_and_b32_e32 v47, 0xffff0000, v48
	v_mul_f32_e32 v46, v50, v46
	v_mul_f32_e32 v47, v50, v47
	v_cvt_pk_bf16_f32 v128, v46, v47
	v_lshlrev_b32_e32 v46, 16, v49
	v_and_b32_e32 v47, 0xffff0000, v49
	v_mul_f32_e32 v46, v50, v46
	v_mul_f32_e32 v47, v50, v47
	v_cvt_pk_bf16_f32 v129, v46, v47
	v_lshlrev_b32_e32 v46, 16, v42
	v_and_b32_e32 v42, 0xffff0000, v42
	v_mul_f32_e32 v46, v50, v46
	v_mul_f32_e32 v42, v50, v42
	v_cvt_pk_bf16_f32 v142, v46, v42
	v_lshlrev_b32_e32 v42, 16, v43
	v_and_b32_e32 v43, 0xffff0000, v43
	v_mul_f32_e32 v42, v50, v42
	v_mul_f32_e32 v43, v50, v43
	v_cvt_pk_bf16_f32 v143, v42, v43
	v_lshlrev_b32_e32 v42, 16, v44
	v_and_b32_e32 v43, 0xffff0000, v44
	v_mul_f32_e32 v42, v50, v42
	v_mul_f32_e32 v43, v50, v43
	v_cvt_pk_bf16_f32 v144, v42, v43
	v_lshlrev_b32_e32 v42, 16, v45
	v_and_b32_e32 v43, 0xffff0000, v45
	v_mul_f32_e32 v42, v50, v42
	v_mul_f32_e32 v43, v50, v43
	v_cvt_pk_bf16_f32 v145, v42, v43
	v_lshlrev_b32_e32 v42, 16, v38
	v_and_b32_e32 v38, 0xffff0000, v38
	v_mul_f32_e32 v42, v50, v42
	v_mul_f32_e32 v38, v50, v38
	v_cvt_pk_bf16_f32 v146, v42, v38
	v_lshlrev_b32_e32 v38, 16, v39
	v_and_b32_e32 v39, 0xffff0000, v39
	v_mul_f32_e32 v38, v50, v38
	v_mul_f32_e32 v39, v50, v39
	v_cvt_pk_bf16_f32 v147, v38, v39
	v_lshlrev_b32_e32 v38, 16, v40
	v_and_b32_e32 v39, 0xffff0000, v40
	v_mul_f32_e32 v38, v50, v38
	v_mul_f32_e32 v39, v50, v39
	v_cvt_pk_bf16_f32 v148, v38, v39
	v_lshlrev_b32_e32 v38, 16, v41
	v_and_b32_e32 v39, 0xffff0000, v41
	v_mul_f32_e32 v38, v50, v38
	v_mul_f32_e32 v39, v50, v39
	v_cvt_pk_bf16_f32 v149, v38, v39
	v_lshlrev_b32_e32 v38, 16, v34
	v_and_b32_e32 v34, 0xffff0000, v34
	v_mul_f32_e32 v38, v50, v38
	v_mul_f32_e32 v34, v50, v34
	v_cvt_pk_bf16_f32 v150, v38, v34
	v_lshlrev_b32_e32 v34, 16, v35
	v_and_b32_e32 v35, 0xffff0000, v35
	v_mul_f32_e32 v34, v50, v34
	v_mul_f32_e32 v35, v50, v35
	v_cvt_pk_bf16_f32 v151, v34, v35
	v_lshlrev_b32_e32 v34, 16, v36
	v_and_b32_e32 v35, 0xffff0000, v36
	v_mul_f32_e32 v34, v50, v34
	v_mul_f32_e32 v35, v50, v35
	v_cvt_pk_bf16_f32 v152, v34, v35
	v_lshlrev_b32_e32 v34, 16, v37
	v_and_b32_e32 v35, 0xffff0000, v37
	v_mul_f32_e32 v34, v50, v34
	v_mul_f32_e32 v35, v50, v35
	v_cvt_pk_bf16_f32 v153, v34, v35
	v_lshlrev_b32_e32 v34, 16, v30
	v_and_b32_e32 v30, 0xffff0000, v30
	v_mul_f32_e32 v34, v50, v34
	v_mul_f32_e32 v30, v50, v30
	v_cvt_pk_bf16_f32 v154, v34, v30
	v_lshlrev_b32_e32 v30, 16, v31
	v_and_b32_e32 v31, 0xffff0000, v31
	v_mul_f32_e32 v30, v50, v30
	v_mul_f32_e32 v31, v50, v31
	v_cvt_pk_bf16_f32 v155, v30, v31
	v_lshlrev_b32_e32 v30, 16, v32
	v_and_b32_e32 v31, 0xffff0000, v32
	v_mul_f32_e32 v30, v50, v30
	v_mul_f32_e32 v31, v50, v31
	v_cvt_pk_bf16_f32 v156, v30, v31
	v_lshlrev_b32_e32 v30, 16, v33
	v_and_b32_e32 v31, 0xffff0000, v33
	v_mul_f32_e32 v30, v50, v30
	v_mul_f32_e32 v31, v50, v31
	v_cvt_pk_bf16_f32 v157, v30, v31
	v_lshlrev_b32_e32 v30, 16, v26
	v_and_b32_e32 v26, 0xffff0000, v26
	v_mul_f32_e32 v30, v50, v30
	v_mul_f32_e32 v26, v50, v26
	v_cvt_pk_bf16_f32 v158, v30, v26
	v_lshlrev_b32_e32 v26, 16, v27
	v_and_b32_e32 v27, 0xffff0000, v27
	v_mul_f32_e32 v26, v50, v26
	v_mul_f32_e32 v27, v50, v27
	v_cvt_pk_bf16_f32 v159, v26, v27
	v_lshlrev_b32_e32 v26, 16, v28
	v_and_b32_e32 v27, 0xffff0000, v28
	v_mul_f32_e32 v26, v50, v26
	v_mul_f32_e32 v27, v50, v27
	v_cvt_pk_bf16_f32 v160, v26, v27
	v_lshlrev_b32_e32 v26, 16, v29
	v_and_b32_e32 v27, 0xffff0000, v29
	v_mul_f32_e32 v26, v50, v26
	v_mul_f32_e32 v27, v50, v27
	v_cvt_pk_bf16_f32 v161, v26, v27
	v_lshlrev_b32_e32 v26, 16, v22
	v_and_b32_e32 v22, 0xffff0000, v22
	v_mul_f32_e32 v26, v50, v26
	v_mul_f32_e32 v22, v50, v22
	v_cvt_pk_bf16_f32 v162, v26, v22
	v_lshlrev_b32_e32 v22, 16, v23
	v_and_b32_e32 v23, 0xffff0000, v23
	v_mul_f32_e32 v22, v50, v22
	v_mul_f32_e32 v23, v50, v23
	v_cvt_pk_bf16_f32 v163, v22, v23
	v_lshlrev_b32_e32 v22, 16, v24
	v_and_b32_e32 v23, 0xffff0000, v24
	v_mul_f32_e32 v22, v50, v22
	v_mul_f32_e32 v23, v50, v23
	v_cvt_pk_bf16_f32 v164, v22, v23
	v_lshlrev_b32_e32 v22, 16, v25
	v_and_b32_e32 v23, 0xffff0000, v25
	v_mul_f32_e32 v22, v50, v22
	v_mul_f32_e32 v23, v50, v23
	v_cvt_pk_bf16_f32 v165, v22, v23
	v_lshlrev_b32_e32 v22, 16, v18
	v_and_b32_e32 v18, 0xffff0000, v18
	v_mul_f32_e32 v22, v50, v22
	v_mul_f32_e32 v18, v50, v18
	v_cvt_pk_bf16_f32 v166, v22, v18
	v_lshlrev_b32_e32 v18, 16, v19
	v_and_b32_e32 v19, 0xffff0000, v19
	v_mul_f32_e32 v18, v50, v18
	v_mul_f32_e32 v19, v50, v19
	v_cvt_pk_bf16_f32 v167, v18, v19
	v_lshlrev_b32_e32 v18, 16, v20
	v_and_b32_e32 v19, 0xffff0000, v20
	v_mul_f32_e32 v18, v50, v18
	v_mul_f32_e32 v19, v50, v19
	v_cvt_pk_bf16_f32 v168, v18, v19
	v_lshlrev_b32_e32 v18, 16, v21
	v_and_b32_e32 v19, 0xffff0000, v21
	v_mul_f32_e32 v18, v50, v18
	v_mul_f32_e32 v19, v50, v19
	v_cvt_pk_bf16_f32 v169, v18, v19
	v_lshlrev_b32_e32 v18, 16, v14
	v_and_b32_e32 v14, 0xffff0000, v14
	v_mul_f32_e32 v18, v50, v18
	v_mul_f32_e32 v14, v50, v14
	v_cvt_pk_bf16_f32 v170, v18, v14
	v_lshlrev_b32_e32 v14, 16, v15
	v_and_b32_e32 v15, 0xffff0000, v15
	v_mul_f32_e32 v14, v50, v14
	v_mul_f32_e32 v15, v50, v15
	v_cvt_pk_bf16_f32 v171, v14, v15
	v_lshlrev_b32_e32 v14, 16, v16
	v_and_b32_e32 v15, 0xffff0000, v16
	v_mul_f32_e32 v14, v50, v14
	v_mul_f32_e32 v15, v50, v15
	v_cvt_pk_bf16_f32 v172, v14, v15
	v_lshlrev_b32_e32 v14, 16, v17
	v_and_b32_e32 v15, 0xffff0000, v17
	v_mul_f32_e32 v14, v50, v14
	v_mul_f32_e32 v15, v50, v15
	v_cvt_pk_bf16_f32 v173, v14, v15
	v_lshlrev_b32_e32 v14, 16, v10
	v_and_b32_e32 v10, 0xffff0000, v10
	v_mul_f32_e32 v14, v50, v14
	v_mul_f32_e32 v10, v50, v10
	v_cvt_pk_bf16_f32 v174, v14, v10
	v_lshlrev_b32_e32 v10, 16, v11
	v_and_b32_e32 v11, 0xffff0000, v11
	v_mul_f32_e32 v10, v50, v10
	v_mul_f32_e32 v11, v50, v11
	v_cvt_pk_bf16_f32 v175, v10, v11
	v_lshlrev_b32_e32 v10, 16, v12
	v_and_b32_e32 v11, 0xffff0000, v12
	v_mul_f32_e32 v10, v50, v10
	v_mul_f32_e32 v11, v50, v11
	v_cvt_pk_bf16_f32 v176, v10, v11
	v_lshlrev_b32_e32 v10, 16, v13
	v_and_b32_e32 v11, 0xffff0000, v13
	v_mul_f32_e32 v10, v50, v10
	v_mul_f32_e32 v11, v50, v11
	v_cvt_pk_bf16_f32 v177, v10, v11
	v_lshlrev_b32_e32 v10, 16, v6
	v_and_b32_e32 v6, 0xffff0000, v6
	v_mul_f32_e32 v10, v50, v10
	v_mul_f32_e32 v6, v50, v6
	v_cvt_pk_bf16_f32 v178, v10, v6
	v_lshlrev_b32_e32 v6, 16, v7
	v_and_b32_e32 v7, 0xffff0000, v7
	v_mul_f32_e32 v6, v50, v6
	v_mul_f32_e32 v7, v50, v7
	v_cvt_pk_bf16_f32 v179, v6, v7
	v_lshlrev_b32_e32 v6, 16, v8
	v_and_b32_e32 v7, 0xffff0000, v8
	v_mul_f32_e32 v6, v50, v6
	v_mul_f32_e32 v7, v50, v7
	v_cvt_pk_bf16_f32 v180, v6, v7
	v_lshlrev_b32_e32 v6, 16, v9
	v_and_b32_e32 v7, 0xffff0000, v9
	v_mul_f32_e32 v6, v50, v6
	v_mul_f32_e32 v7, v50, v7
	v_cvt_pk_bf16_f32 v181, v6, v7
	v_lshlrev_b32_e32 v6, 16, v2
	v_and_b32_e32 v2, 0xffff0000, v2
	v_mul_f32_e32 v6, v50, v6
	v_mul_f32_e32 v2, v50, v2
	v_cvt_pk_bf16_f32 v182, v6, v2
	v_lshlrev_b32_e32 v2, 16, v3
	v_and_b32_e32 v3, 0xffff0000, v3
	v_mul_f32_e32 v2, v50, v2
	v_mul_f32_e32 v3, v50, v3
	v_cvt_pk_bf16_f32 v183, v2, v3
	v_lshlrev_b32_e32 v2, 16, v4
	v_and_b32_e32 v3, 0xffff0000, v4
	v_mul_f32_e32 v2, v50, v2
	v_mul_f32_e32 v3, v50, v3
	v_cvt_pk_bf16_f32 v184, v2, v3
	v_lshlrev_b32_e32 v2, 16, v5
	v_and_b32_e32 v3, 0xffff0000, v5
	v_mul_f32_e32 v2, v50, v2
	v_mul_f32_e32 v3, v50, v3
	v_cvt_pk_bf16_f32 v185, v2, v3
	v_lshl_add_u64 v[2:3], s[20:21], 0, v[198:199]
	s_mov_b64 s[14:15], 0x1c000
	v_lshl_add_u64 v[206:207], v[2:3], 0, s[14:15]
	v_mov_b64_e32 v[2:3], s[42:43]
	v_mov_b32_e32 v16, v1
	v_mov_b32_e32 v17, v1
	v_mad_i64_i32 v[208:209], s[14:15], v200, s11, v[2:3]
	v_mov_b32_e32 v2, v1
	v_mov_b32_e32 v3, v1
	v_mov_b32_e32 v4, v1
	v_mov_b32_e32 v5, v1
	v_mov_b32_e32 v6, v1
	v_mov_b32_e32 v7, v1
	v_mov_b32_e32 v8, v1
	v_mov_b32_e32 v9, v1
	v_mov_b32_e32 v10, v1
	v_mov_b32_e32 v11, v1
	v_mov_b32_e32 v12, v1
	v_mov_b32_e32 v13, v1
	v_mov_b32_e32 v14, v1
	v_mov_b32_e32 v15, v1
	v_mov_b64_e32 v[32:33], v[16:17]
	v_mov_b64_e32 v[48:49], v[16:17]
	v_mov_b64_e32 v[64:65], v[16:17]
	s_lshr_b32 s5, s11, 6
	v_mov_b32_e32 v224, 0
	v_mov_b32_e32 v223, 0xf149f2ca
	s_mov_b32 s11, 4
	v_mov_b64_e32 v[30:31], v[14:15]
	v_mov_b64_e32 v[28:29], v[12:13]
	v_mov_b64_e32 v[26:27], v[10:11]
	v_mov_b64_e32 v[24:25], v[8:9]
	v_mov_b64_e32 v[22:23], v[6:7]
	v_mov_b64_e32 v[20:21], v[4:5]
	v_mov_b64_e32 v[18:19], v[2:3]
	v_mov_b64_e32 v[46:47], v[14:15]
	v_mov_b64_e32 v[44:45], v[12:13]
	v_mov_b64_e32 v[42:43], v[10:11]
	v_mov_b64_e32 v[40:41], v[8:9]
	v_mov_b64_e32 v[38:39], v[6:7]
	v_mov_b64_e32 v[36:37], v[4:5]
	v_mov_b64_e32 v[34:35], v[2:3]
	v_mov_b64_e32 v[62:63], v[14:15]
	v_mov_b64_e32 v[60:61], v[12:13]
	v_mov_b64_e32 v[58:59], v[10:11]
	v_mov_b64_e32 v[56:57], v[8:9]
	v_mov_b64_e32 v[54:55], v[6:7]
	v_mov_b64_e32 v[52:53], v[4:5]
	v_mov_b64_e32 v[50:51], v[2:3]
	v_readlane_b32 s33, v254, 35
	s_mov_b32 s34, 0x18000
	s_waitcnt vmcnt(5)
	v_lshlrev_b32_e32 v204, 1, v190
	s_lshl_b32 s13, s5, 7
	v_mul_lo_u32 v207, v188, s13
	v_add_u32_e32 v207, v207, v194
	s_add_u32 s66, s20, 0x12000
	s_addc_u32 s67, s21, 0
	s_add_u32 s74, s20, 0x14000
	s_addc_u32 s75, s21, 0
	s_add_u32 s76, s20, 0x16000
	s_addc_u32 s77, s21, 0
	s_add_u32 s68, s42, 0x180
	s_addc_u32 s69, s43, 0
	s_lshl_b32 s13, s5, 13
	s_add_u32 s78, s68, s13
	s_addc_u32 s79, s69, 0
	v_readfirstlane_b32 s13, v190
	s_nop 3
	s_mul_i32 s13, s13, 7
	s_cmp_lt_u32 s13, 14336
	s_cselect_b32 vcc_lo, 0, 1024
	s_add_i32 s13, s13, vcc_lo
	s_add_i32 s13, s13, 132096
	v_mbcnt_lo_u32_b32 v217, -1, 0
	v_mbcnt_hi_u32_b32 v217, -1, v217
	v_lshl_add_u32 v217, v217, 2, s13
	ds_write_b32 v217, v188
	ds_write_b32 v217, v189 offset:256
	ds_write_b32 v217, v190 offset:512
	ds_write_b32 v217, v191 offset:768
	ds_write_b32 v217, v192 offset:1024
	ds_write_b32 v217, v193 offset:1280
	ds_write_b32 v217, v194 offset:1536
	ds_write_b32 v217, v196 offset:1792
	ds_write_b32 v217, v197 offset:2048
	ds_write_b32 v217, v198 offset:2304
	ds_write_b32 v217, v199 offset:2560
	ds_write_b32 v217, v200 offset:2816
	ds_write_b32 v217, v202 offset:3072
	ds_write_b32 v217, v203 offset:3328
	v_mov_b32_e32 v188, 0
	v_mov_b32_e32 v189, 0
	v_mov_b32_e32 v190, 0
	v_mov_b32_e32 v191, 0
	v_mov_b32_e32 v192, 0
	v_mov_b32_e32 v193, 0
	v_mov_b32_e32 v194, 0
	v_mov_b32_e32 v195, 0
	v_mov_b32_e32 v196, 0
	v_mov_b32_e32 v197, 0
	v_mov_b32_e32 v198, 0
	v_mov_b32_e32 v199, 0
	v_mov_b32_e32 v200, 0
	v_mov_b32_e32 v201, 0
	v_mov_b32_e32 v202, 0
	v_mov_b32_e32 v203, 0
	s_mov_b32 s70, 0
	s_mov_b32 s71, 44032
	s_mov_b32 s72, 44032
	s_mov_b32 s11, -1
	s_add_i32 s13, s11, 2
	s_cmp_ge_u32 s13, s5
	s_cbranch_scc1 .Latt3_wskip_1
	v_add_u32_e32 v206, s72, v219
	v_add_u32_e32 v208, s72, v220
	v_add_u32_e32 v186, s72, v221
	v_add_u32_e32 v187, s72, v222
	s_add_i32 s13, s11, 3
	s_cmp_ge_u32 s13, s5
	s_cbranch_scc1 .Latt3_wtail_2
	s_waitcnt vmcnt(9)
	ds_write_b128 v206, v[102:105]
	s_waitcnt vmcnt(8)
	ds_write_b128 v208, v[106:109]
	s_waitcnt vmcnt(7)
	ds_write_b128 v186, v[114:117]
	s_waitcnt vmcnt(6)
	ds_write_b128 v187, v[98:101] offset:25600
	s_waitcnt vmcnt(5)
	ds_write_b128 v187, v[110:113] offset:34816
	s_branch .Latt3_wld_3

.Latt3_A_loop:
	v_add_u32_e32 v209, s70, v215
	v_add_u32_e32 v205, s70, v216
	ds_read_b128 v[226:229], v209
	ds_read_b128 v[236:239], v209 offset:12800
	ds_read_b128 v[240:243], v209 offset:32
	ds_read_b128 v[244:247], v209 offset:12832
	ds_read_b128 v[248:251], v209 offset:64
	ds_read_b128 v[210:213], v209 offset:12864
	s_waitcnt lgkmcnt(5)
	v_mfma_f32_32x32x16_bf16 v[82:97], v[226:229], v[126:129], v[188:203]
	ds_read_b128 v[226:229], v209 offset:96
	s_waitcnt lgkmcnt(5)
	v_mfma_f32_32x32x16_bf16 v[66:81], v[236:239], v[126:129], v[188:203]
	ds_read_b128 v[236:239], v209 offset:12896
	s_waitcnt lgkmcnt(5)
	v_mfma_f32_32x32x16_bf16 v[82:97], v[240:243], v[142:145], v[82:97]
	ds_read_b128 v[240:243], v209 offset:128
	s_waitcnt lgkmcnt(5)
	v_mfma_f32_32x32x16_bf16 v[66:81], v[244:247], v[142:145], v[66:81]
	ds_read_b128 v[244:247], v209 offset:12928
	s_waitcnt lgkmcnt(5)
	v_mfma_f32_32x32x16_bf16 v[82:97], v[248:251], v[146:149], v[82:97]
	ds_read_b128 v[248:251], v209 offset:160
	s_waitcnt lgkmcnt(5)
	v_mfma_f32_32x32x16_bf16 v[66:81], v[210:213], v[146:149], v[66:81]
	ds_read_b128 v[210:213], v209 offset:12960
	s_waitcnt lgkmcnt(5)
	v_mfma_f32_32x32x16_bf16 v[82:97], v[226:229], v[150:153], v[82:97]
	ds_read_b128 v[226:229], v209 offset:192
	s_waitcnt lgkmcnt(5)
	v_mfma_f32_32x32x16_bf16 v[66:81], v[236:239], v[150:153], v[66:81]
	ds_read_b128 v[236:239], v209 offset:12992
	s_waitcnt lgkmcnt(5)
	v_mfma_f32_32x32x16_bf16 v[82:97], v[240:243], v[154:157], v[82:97]
	ds_read_b128 v[240:243], v209 offset:224
	s_waitcnt lgkmcnt(5)
	v_mfma_f32_32x32x16_bf16 v[66:81], v[244:247], v[154:157], v[66:81]
	ds_read_b128 v[244:247], v209 offset:13024
	s_waitcnt lgkmcnt(5)
	v_mfma_f32_32x32x16_bf16 v[82:97], v[248:251], v[158:161], v[82:97]
	ds_read_b128 v[248:251], v209 offset:256
	s_waitcnt lgkmcnt(5)
	v_mfma_f32_32x32x16_bf16 v[66:81], v[210:213], v[158:161], v[66:81]
	ds_read_b128 v[210:213], v209 offset:13056
	s_waitcnt lgkmcnt(5)
	v_mfma_f32_32x32x16_bf16 v[82:97], v[226:229], v[162:165], v[82:97]
	ds_read_b128 v[226:229], v209 offset:288
	s_waitcnt lgkmcnt(5)
	v_mfma_f32_32x32x16_bf16 v[66:81], v[236:239], v[162:165], v[66:81]
	ds_read_b128 v[236:239], v209 offset:13088
	s_waitcnt lgkmcnt(5)
	v_mfma_f32_32x32x16_bf16 v[82:97], v[240:243], v[166:169], v[82:97]
	ds_read_b128 v[240:243], v209 offset:320
	s_waitcnt lgkmcnt(5)
	v_mfma_f32_32x32x16_bf16 v[66:81], v[244:247], v[166:169], v[66:81]
	ds_read_b128 v[244:247], v209 offset:13120
	s_waitcnt lgkmcnt(5)
	v_mfma_f32_32x32x16_bf16 v[82:97], v[248:251], v[170:173], v[82:97]
	ds_read_b128 v[248:251], v209 offset:352
	s_waitcnt lgkmcnt(5)
	v_mfma_f32_32x32x16_bf16 v[66:81], v[210:213], v[170:173], v[66:81]
	ds_read_b128 v[210:213], v209 offset:13152
	s_waitcnt lgkmcnt(5)
	v_mfma_f32_32x32x16_bf16 v[82:97], v[226:229], v[174:177], v[82:97]
	s_waitcnt lgkmcnt(4)
	v_mfma_f32_32x32x16_bf16 v[66:81], v[236:239], v[174:177], v[66:81]
	s_waitcnt lgkmcnt(3)
	v_mfma_f32_32x32x16_bf16 v[82:97], v[240:243], v[178:181], v[82:97]
	s_waitcnt lgkmcnt(2)
	v_mfma_f32_32x32x16_bf16 v[66:81], v[244:247], v[178:181], v[66:81]
	s_waitcnt lgkmcnt(1)
	v_mfma_f32_32x32x16_bf16 v[82:97], v[248:251], v[182:185], v[82:97]
	s_waitcnt lgkmcnt(0)
	v_mfma_f32_32x32x16_bf16 v[66:81], v[210:213], v[182:185], v[66:81]
	s_setprio 2
	ds_read_b128 v[236:239], v205 offset:25600
	ds_read_b128 v[240:243], v205 offset:30208
	ds_read_b128 v[244:247], v205 offset:34816
	ds_read_b128 v[248:251], v205 offset:39424
	ds_read_b128 v[210:213], v205 offset:25632
	s_nop 4
	v_max_f32_e32 v186, v83, v83
	v_max_f32_e32 v187, v82, v82
	v_max_f32_e32 v186, v187, v186
	v_max3_f32 v186, v186, v84, v85
	v_max3_f32 v186, v186, v86, v87
	v_max3_f32 v186, v186, v88, v89
	v_max3_f32 v186, v186, v90, v91
	v_max3_f32 v186, v186, v92, v93
	v_max3_f32 v186, v186, v94, v95
	v_max3_f32 v186, v186, v96, v97
	v_max3_f32 v186, v186, v66, v67
	v_max3_f32 v186, v186, v68, v69
	v_max3_f32 v186, v186, v70, v71
	v_max3_f32 v186, v186, v72, v73
	v_max3_f32 v186, v186, v74, v75
	v_max3_f32 v186, v186, v76, v77
	v_max3_f32 v186, v186, v78, v79
	v_max3_f32 v186, v186, v80, v81
	v_mov_b32_e32 v187, v186
	s_nop 1
	v_permlane32_swap_b32_e32 v186, v187
	v_max_f32_e32 v187, v186, v187
	v_sub_f32_e32 v187, v187, v188
	v_add_f32_e32 v186, 0x41380000, v223
	v_cmp_gt_f32_e32 vcc, v187, v186
	s_cbranch_vccz .Latt3_nr_5
	v_max_f32_e32 v186, v187, v187
	v_max_f32_e32 v187, v223, v223
	v_max_f32_e32 v187, v187, v186
	v_sub_f32_e32 v186, v223, v187
	v_exp_f32_e32 v186, v186
	v_mov_b32_e32 v223, v187
	v_pk_mul_f32 v[64:65], v[64:65], v[186:187] op_sel_hi:[1,0]
	v_pk_mul_f32 v[62:63], v[62:63], v[186:187] op_sel_hi:[1,0]
	v_pk_mul_f32 v[60:61], v[60:61], v[186:187] op_sel_hi:[1,0]
	v_pk_mul_f32 v[58:59], v[58:59], v[186:187] op_sel_hi:[1,0]
	v_pk_mul_f32 v[56:57], v[56:57], v[186:187] op_sel_hi:[1,0]
	v_pk_mul_f32 v[54:55], v[54:55], v[186:187] op_sel_hi:[1,0]
	v_pk_mul_f32 v[52:53], v[52:53], v[186:187] op_sel_hi:[1,0]
	v_pk_mul_f32 v[50:51], v[50:51], v[186:187] op_sel_hi:[1,0]
	v_pk_mul_f32 v[48:49], v[48:49], v[186:187] op_sel_hi:[1,0]
	v_pk_mul_f32 v[46:47], v[46:47], v[186:187] op_sel_hi:[1,0]
	v_pk_mul_f32 v[44:45], v[44:45], v[186:187] op_sel_hi:[1,0]
	v_pk_mul_f32 v[42:43], v[42:43], v[186:187] op_sel_hi:[1,0]
	v_pk_mul_f32 v[40:41], v[40:41], v[186:187] op_sel_hi:[1,0]
	v_pk_mul_f32 v[38:39], v[38:39], v[186:187] op_sel_hi:[1,0]
	v_pk_mul_f32 v[36:37], v[36:37], v[186:187] op_sel_hi:[1,0]
	v_pk_mul_f32 v[34:35], v[34:35], v[186:187] op_sel_hi:[1,0]
	v_pk_mul_f32 v[32:33], v[32:33], v[186:187] op_sel_hi:[1,0]
	v_pk_mul_f32 v[30:31], v[30:31], v[186:187] op_sel_hi:[1,0]
	v_pk_mul_f32 v[28:29], v[28:29], v[186:187] op_sel_hi:[1,0]
	v_pk_mul_f32 v[26:27], v[26:27], v[186:187] op_sel_hi:[1,0]
	v_pk_mul_f32 v[24:25], v[24:25], v[186:187] op_sel_hi:[1,0]
	v_pk_mul_f32 v[22:23], v[22:23], v[186:187] op_sel_hi:[1,0]
	v_pk_mul_f32 v[20:21], v[20:21], v[186:187] op_sel_hi:[1,0]
	v_pk_mul_f32 v[18:19], v[18:19], v[186:187] op_sel_hi:[1,0]
	v_pk_mul_f32 v[16:17], v[16:17], v[186:187] op_sel_hi:[1,0]
	v_pk_mul_f32 v[14:15], v[14:15], v[186:187] op_sel_hi:[1,0]
	v_pk_mul_f32 v[12:13], v[12:13], v[186:187] op_sel_hi:[1,0]
	v_pk_mul_f32 v[10:11], v[10:11], v[186:187] op_sel_hi:[1,0]
	v_pk_mul_f32 v[8:9], v[8:9], v[186:187] op_sel_hi:[1,0]
	v_pk_mul_f32 v[6:7], v[6:7], v[186:187] op_sel_hi:[1,0]
	v_pk_mul_f32 v[4:5], v[4:5], v[186:187] op_sel_hi:[1,0]
	v_pk_mul_f32 v[2:3], v[2:3], v[186:187] op_sel_hi:[1,0]
	v_mul_f32_e32 v224, v224, v186
	v_add_f32_e32 v186, v187, v188
	v_sub_f32_e32 v82, v82, v186
	v_sub_f32_e32 v83, v83, v186
	v_sub_f32_e32 v84, v84, v186
	v_sub_f32_e32 v85, v85, v186
	v_sub_f32_e32 v86, v86, v186
	v_sub_f32_e32 v87, v87, v186
	v_sub_f32_e32 v88, v88, v186
	v_sub_f32_e32 v89, v89, v186
	v_sub_f32_e32 v90, v90, v186
	v_sub_f32_e32 v91, v91, v186
	v_sub_f32_e32 v92, v92, v186
	v_sub_f32_e32 v93, v93, v186
	v_sub_f32_e32 v94, v94, v186
	v_sub_f32_e32 v95, v95, v186
	v_sub_f32_e32 v96, v96, v186
	v_sub_f32_e32 v97, v97, v186
	v_sub_f32_e32 v66, v66, v186
	v_sub_f32_e32 v67, v67, v186
	v_sub_f32_e32 v68, v68, v186
	v_sub_f32_e32 v69, v69, v186
	v_sub_f32_e32 v70, v70, v186
	v_sub_f32_e32 v71, v71, v186
	v_sub_f32_e32 v72, v72, v186
	v_sub_f32_e32 v73, v73, v186
	v_sub_f32_e32 v74, v74, v186
	v_sub_f32_e32 v75, v75, v186
	v_sub_f32_e32 v76, v76, v186
	v_sub_f32_e32 v77, v77, v186
	v_sub_f32_e32 v78, v78, v186
	v_sub_f32_e32 v79, v79, v186
	v_sub_f32_e32 v80, v80, v186
	v_sub_f32_e32 v81, v81, v186
	v_sub_f32_e32 v188, 0, v187
	v_sub_f32_e32 v189, 0, v187
	v_sub_f32_e32 v190, 0, v187
	v_sub_f32_e32 v191, 0, v187
	v_sub_f32_e32 v192, 0, v187
	v_sub_f32_e32 v193, 0, v187
	v_sub_f32_e32 v194, 0, v187
	v_sub_f32_e32 v195, 0, v187
	v_sub_f32_e32 v196, 0, v187
	v_sub_f32_e32 v197, 0, v187
	v_sub_f32_e32 v198, 0, v187
	v_sub_f32_e32 v199, 0, v187
	v_sub_f32_e32 v200, 0, v187
	v_sub_f32_e32 v201, 0, v187
	v_sub_f32_e32 v202, 0, v187
	v_sub_f32_e32 v203, 0, v187
.Latt3_nr_5:
	v_exp_f32_e32 v82, v82
	v_exp_f32_e32 v83, v83
	v_exp_f32_e32 v84, v84
	v_exp_f32_e32 v85, v85
	v_exp_f32_e32 v86, v86
	v_exp_f32_e32 v87, v87
	v_exp_f32_e32 v88, v88
	v_exp_f32_e32 v89, v89
	v_cvt_pk_bf16_f32 v226, v82, v83
	v_cvt_pk_bf16_f32 v227, v84, v85
	v_cvt_pk_bf16_f32 v228, v86, v87
	v_cvt_pk_bf16_f32 v229, v88, v89
	s_nop 1
	s_waitcnt lgkmcnt(4)
	v_mfma_f32_32x32x16_bf16 v[50:65], v[236:239], v[226:229], v[50:65]
	ds_read_b128 v[236:239], v205 offset:30240
	v_exp_f32_e32 v90, v90
	v_exp_f32_e32 v91, v91
	v_exp_f32_e32 v92, v92
	v_exp_f32_e32 v93, v93
	s_waitcnt lgkmcnt(4)
	v_mfma_f32_32x32x16_bf16 v[34:49], v[240:243], v[226:229], v[34:49]
	ds_read_b128 v[240:243], v205 offset:34848
	v_exp_f32_e32 v94, v94
	v_exp_f32_e32 v95, v95
	v_exp_f32_e32 v96, v96
	v_exp_f32_e32 v97, v97
	s_waitcnt lgkmcnt(4)
	v_mfma_f32_32x32x16_bf16 v[18:33], v[244:247], v[226:229], v[18:33]
	ds_read_b128 v[244:247], v205 offset:39456
	v_add_f32_e32 v186, 0, v82
	v_add_f32_e32 v187, 0, v86
	v_add_f32_e32 v186, v83, v186
	v_add_f32_e32 v187, v87, v187
	s_waitcnt lgkmcnt(4)
	v_mfma_f32_32x32x16_bf16 v[2:17], v[248:251], v[226:229], v[2:17]
	ds_read_b128 v[248:251], v205 offset:25664
	v_add_f32_e32 v186, v84, v186
	v_add_f32_e32 v187, v88, v187
	v_add_f32_e32 v186, v85, v186
	v_add_f32_e32 v187, v89, v187
	v_cvt_pk_bf16_f32 v226, v90, v91
	v_cvt_pk_bf16_f32 v227, v92, v93
	v_cvt_pk_bf16_f32 v228, v94, v95
	v_cvt_pk_bf16_f32 v229, v96, v97
	s_nop 1
	s_waitcnt lgkmcnt(4)
	v_mfma_f32_32x32x16_bf16 v[50:65], v[210:213], v[226:229], v[50:65]
	ds_read_b128 v[210:213], v205 offset:30272
	v_exp_f32_e32 v66, v66
	v_exp_f32_e32 v67, v67
	v_exp_f32_e32 v68, v68
	v_exp_f32_e32 v69, v69
	s_waitcnt lgkmcnt(4)
	v_mfma_f32_32x32x16_bf16 v[34:49], v[236:239], v[226:229], v[34:49]
	ds_read_b128 v[236:239], v205 offset:34880
	v_exp_f32_e32 v70, v70
	v_exp_f32_e32 v71, v71
	v_exp_f32_e32 v72, v72
	v_exp_f32_e32 v73, v73
	s_waitcnt lgkmcnt(4)
	v_mfma_f32_32x32x16_bf16 v[18:33], v[240:243], v[226:229], v[18:33]
	ds_read_b128 v[240:243], v205 offset:39488
	v_add_f32_e32 v186, v90, v186
	v_add_f32_e32 v187, v94, v187
	v_add_f32_e32 v186, v91, v186
	v_add_f32_e32 v187, v95, v187
	s_waitcnt lgkmcnt(4)
	v_mfma_f32_32x32x16_bf16 v[2:17], v[244:247], v[226:229], v[2:17]
	ds_read_b128 v[244:247], v205 offset:25696
	v_add_f32_e32 v186, v92, v186
	v_add_f32_e32 v187, v96, v187
	v_add_f32_e32 v186, v93, v186
	v_add_f32_e32 v187, v97, v187
	v_cvt_pk_bf16_f32 v226, v66, v67
	v_cvt_pk_bf16_f32 v227, v68, v69
	v_cvt_pk_bf16_f32 v228, v70, v71
	v_cvt_pk_bf16_f32 v229, v72, v73
	s_nop 1
	s_waitcnt lgkmcnt(4)
	v_mfma_f32_32x32x16_bf16 v[50:65], v[248:251], v[226:229], v[50:65]
	ds_read_b128 v[248:251], v205 offset:30304
	v_exp_f32_e32 v74, v74
	v_exp_f32_e32 v75, v75
	v_exp_f32_e32 v76, v76
	v_exp_f32_e32 v77, v77
	s_waitcnt lgkmcnt(4)
	v_mfma_f32_32x32x16_bf16 v[34:49], v[210:213], v[226:229], v[34:49]
	ds_read_b128 v[210:213], v205 offset:34912
	v_exp_f32_e32 v78, v78
	v_exp_f32_e32 v79, v79
	v_exp_f32_e32 v80, v80
	v_exp_f32_e32 v81, v81
	s_waitcnt lgkmcnt(4)
	v_mfma_f32_32x32x16_bf16 v[18:33], v[236:239], v[226:229], v[18:33]
	ds_read_b128 v[236:239], v205 offset:39520
	v_add_f32_e32 v186, v66, v186
	v_add_f32_e32 v187, v70, v187
	v_add_f32_e32 v186, v67, v186
	v_add_f32_e32 v187, v71, v187
	s_waitcnt lgkmcnt(4)
	v_mfma_f32_32x32x16_bf16 v[2:17], v[240:243], v[226:229], v[2:17]
	v_add_f32_e32 v186, v68, v186
	v_add_f32_e32 v187, v72, v187
	v_add_f32_e32 v186, v69, v186
	v_add_f32_e32 v187, v73, v187
	v_cvt_pk_bf16_f32 v226, v74, v75
	v_cvt_pk_bf16_f32 v227, v76, v77
	v_cvt_pk_bf16_f32 v228, v78, v79
	v_cvt_pk_bf16_f32 v229, v80, v81
	s_nop 1
	s_waitcnt lgkmcnt(3)
	v_mfma_f32_32x32x16_bf16 v[50:65], v[244:247], v[226:229], v[50:65]
	v_add_f32_e32 v186, v74, v186
	v_add_f32_e32 v187, v78, v187
	s_waitcnt lgkmcnt(2)
	v_mfma_f32_32x32x16_bf16 v[34:49], v[248:251], v[226:229], v[34:49]
	v_add_f32_e32 v186, v75, v186
	v_add_f32_e32 v187, v79, v187
	s_waitcnt lgkmcnt(1)
	v_mfma_f32_32x32x16_bf16 v[18:33], v[210:213], v[226:229], v[18:33]
	v_add_f32_e32 v186, v76, v186
	v_add_f32_e32 v187, v80, v187
	s_waitcnt lgkmcnt(0)
	s_barrier
	v_mfma_f32_32x32x16_bf16 v[2:17], v[236:239], v[226:229], v[2:17]
	v_add_f32_e32 v186, v77, v186
	v_add_f32_e32 v187, v81, v187
	v_add_f32_e32 v186, v186, v187
	v_add_f32_e32 v225, v224, v186
	s_setprio 0
	s_add_i32 s13, s11, 2
	s_cmp_ge_u32 s13, s5
	s_cbranch_scc1 .Latt3_wskip_6
	v_add_u32_e32 v206, s72, v219
	v_add_u32_e32 v208, s72, v220
	v_add_u32_e32 v186, s72, v221
	v_add_u32_e32 v187, s72, v222
	s_add_i32 s13, s11, 3
	s_cmp_ge_u32 s13, s5
	s_cbranch_scc1 .Latt3_wtail_7
	s_waitcnt vmcnt(9)
	ds_write_b128 v206, v[118:121]
	s_waitcnt vmcnt(8)
	ds_write_b128 v208, v[122:125]
	s_waitcnt vmcnt(7)
	ds_write_b128 v186, v[130:133]
	s_waitcnt vmcnt(6)
	ds_write_b128 v187, v[134:137] offset:25600
	s_waitcnt vmcnt(5)
	ds_write_b128 v187, v[138:141] offset:34816
	s_branch .Latt3_wld_8

.Latt3_wdone_9:
.Latt3_wskip_6:
	s_mov_b32 s13, s70
	s_mov_b32 s70, s71
	s_mov_b32 s71, s72
	s_mov_b32 s72, s13
	s_add_i32 s11, s11, 1
	v_add_u32_e32 v209, s70, v215
	v_add_u32_e32 v205, s70, v216
	ds_read_b128 v[226:229], v209
	ds_read_b128 v[236:239], v209 offset:12800
	ds_read_b128 v[240:243], v209 offset:32
	ds_read_b128 v[244:247], v209 offset:12832
	ds_read_b128 v[248:251], v209 offset:64
	ds_read_b128 v[210:213], v209 offset:12864
	s_waitcnt lgkmcnt(5)
	v_mfma_f32_32x32x16_bf16 v[82:97], v[226:229], v[126:129], v[188:203]
	ds_read_b128 v[226:229], v209 offset:96
	s_waitcnt lgkmcnt(5)
	v_mfma_f32_32x32x16_bf16 v[66:81], v[236:239], v[126:129], v[188:203]
	ds_read_b128 v[236:239], v209 offset:12896
	s_waitcnt lgkmcnt(5)
	v_mfma_f32_32x32x16_bf16 v[82:97], v[240:243], v[142:145], v[82:97]
	ds_read_b128 v[240:243], v209 offset:128
	s_waitcnt lgkmcnt(5)
	v_mfma_f32_32x32x16_bf16 v[66:81], v[244:247], v[142:145], v[66:81]
	ds_read_b128 v[244:247], v209 offset:12928
	s_waitcnt lgkmcnt(5)
	v_mfma_f32_32x32x16_bf16 v[82:97], v[248:251], v[146:149], v[82:97]
	ds_read_b128 v[248:251], v209 offset:160
	s_waitcnt lgkmcnt(5)
	v_mfma_f32_32x32x16_bf16 v[66:81], v[210:213], v[146:149], v[66:81]
	ds_read_b128 v[210:213], v209 offset:12960
	s_waitcnt lgkmcnt(5)
	v_mfma_f32_32x32x16_bf16 v[82:97], v[226:229], v[150:153], v[82:97]
	ds_read_b128 v[226:229], v209 offset:192
	s_waitcnt lgkmcnt(5)
	v_mfma_f32_32x32x16_bf16 v[66:81], v[236:239], v[150:153], v[66:81]
	ds_read_b128 v[236:239], v209 offset:12992
	s_waitcnt lgkmcnt(5)
	v_mfma_f32_32x32x16_bf16 v[82:97], v[240:243], v[154:157], v[82:97]
	ds_read_b128 v[240:243], v209 offset:224
	s_waitcnt lgkmcnt(5)
	v_mfma_f32_32x32x16_bf16 v[66:81], v[244:247], v[154:157], v[66:81]
	ds_read_b128 v[244:247], v209 offset:13024
	s_waitcnt lgkmcnt(5)
	v_mfma_f32_32x32x16_bf16 v[82:97], v[248:251], v[158:161], v[82:97]
	ds_read_b128 v[248:251], v209 offset:256
	s_waitcnt lgkmcnt(5)
	v_mfma_f32_32x32x16_bf16 v[66:81], v[210:213], v[158:161], v[66:81]
	ds_read_b128 v[210:213], v209 offset:13056
	s_waitcnt lgkmcnt(5)
	v_mfma_f32_32x32x16_bf16 v[82:97], v[226:229], v[162:165], v[82:97]
	ds_read_b128 v[226:229], v209 offset:288
	s_waitcnt lgkmcnt(5)
	v_mfma_f32_32x32x16_bf16 v[66:81], v[236:239], v[162:165], v[66:81]
	ds_read_b128 v[236:239], v209 offset:13088
	s_waitcnt lgkmcnt(5)
	v_mfma_f32_32x32x16_bf16 v[82:97], v[240:243], v[166:169], v[82:97]
	ds_read_b128 v[240:243], v209 offset:320
	s_waitcnt lgkmcnt(5)
	v_mfma_f32_32x32x16_bf16 v[66:81], v[244:247], v[166:169], v[66:81]
	ds_read_b128 v[244:247], v209 offset:13120
	s_waitcnt lgkmcnt(5)
	v_mfma_f32_32x32x16_bf16 v[82:97], v[248:251], v[170:173], v[82:97]
	ds_read_b128 v[248:251], v209 offset:352
	s_waitcnt lgkmcnt(5)
	v_mfma_f32_32x32x16_bf16 v[66:81], v[210:213], v[170:173], v[66:81]
	ds_read_b128 v[210:213], v209 offset:13152
	s_waitcnt lgkmcnt(5)
	v_mfma_f32_32x32x16_bf16 v[82:97], v[226:229], v[174:177], v[82:97]
	s_waitcnt lgkmcnt(4)
	v_mfma_f32_32x32x16_bf16 v[66:81], v[236:239], v[174:177], v[66:81]
	s_waitcnt lgkmcnt(3)
	v_mfma_f32_32x32x16_bf16 v[82:97], v[240:243], v[178:181], v[82:97]
	s_waitcnt lgkmcnt(2)
	v_mfma_f32_32x32x16_bf16 v[66:81], v[244:247], v[178:181], v[66:81]
	s_waitcnt lgkmcnt(1)
	v_mfma_f32_32x32x16_bf16 v[82:97], v[248:251], v[182:185], v[82:97]
	s_waitcnt lgkmcnt(0)
	v_mfma_f32_32x32x16_bf16 v[66:81], v[210:213], v[182:185], v[66:81]
	s_setprio 2
	ds_read_b128 v[236:239], v205 offset:25600
	ds_read_b128 v[240:243], v205 offset:30208
	ds_read_b128 v[244:247], v205 offset:34816
	ds_read_b128 v[248:251], v205 offset:39424
	ds_read_b128 v[210:213], v205 offset:25632
	s_nop 4
	v_max_f32_e32 v186, v83, v83
	v_max_f32_e32 v187, v82, v82
	v_max_f32_e32 v186, v187, v186
	v_max3_f32 v186, v186, v84, v85
	v_max3_f32 v186, v186, v86, v87
	v_max3_f32 v186, v186, v88, v89
	v_max3_f32 v186, v186, v90, v91
	v_max3_f32 v186, v186, v92, v93
	v_max3_f32 v186, v186, v94, v95
	v_max3_f32 v186, v186, v96, v97
	v_max3_f32 v186, v186, v66, v67
	v_max3_f32 v186, v186, v68, v69
	v_max3_f32 v186, v186, v70, v71
	v_max3_f32 v186, v186, v72, v73
	v_max3_f32 v186, v186, v74, v75
	v_max3_f32 v186, v186, v76, v77
	v_max3_f32 v186, v186, v78, v79
	v_max3_f32 v186, v186, v80, v81
	v_mov_b32_e32 v187, v186
	s_nop 1
	v_permlane32_swap_b32_e32 v186, v187
	v_max_f32_e32 v187, v186, v187
	v_sub_f32_e32 v187, v187, v188
	v_add_f32_e32 v186, 0x41380000, v223
	v_cmp_gt_f32_e32 vcc, v187, v186
	s_cbranch_vccz .Latt3_nr_10
	v_max_f32_e32 v186, v187, v187
	v_max_f32_e32 v187, v223, v223
	v_max_f32_e32 v187, v187, v186
	v_sub_f32_e32 v186, v223, v187
	v_exp_f32_e32 v186, v186
	v_mov_b32_e32 v223, v187
	v_pk_mul_f32 v[64:65], v[64:65], v[186:187] op_sel_hi:[1,0]
	v_pk_mul_f32 v[62:63], v[62:63], v[186:187] op_sel_hi:[1,0]
	v_pk_mul_f32 v[60:61], v[60:61], v[186:187] op_sel_hi:[1,0]
	v_pk_mul_f32 v[58:59], v[58:59], v[186:187] op_sel_hi:[1,0]
	v_pk_mul_f32 v[56:57], v[56:57], v[186:187] op_sel_hi:[1,0]
	v_pk_mul_f32 v[54:55], v[54:55], v[186:187] op_sel_hi:[1,0]
	v_pk_mul_f32 v[52:53], v[52:53], v[186:187] op_sel_hi:[1,0]
	v_pk_mul_f32 v[50:51], v[50:51], v[186:187] op_sel_hi:[1,0]
	v_pk_mul_f32 v[48:49], v[48:49], v[186:187] op_sel_hi:[1,0]
	v_pk_mul_f32 v[46:47], v[46:47], v[186:187] op_sel_hi:[1,0]
	v_pk_mul_f32 v[44:45], v[44:45], v[186:187] op_sel_hi:[1,0]
	v_pk_mul_f32 v[42:43], v[42:43], v[186:187] op_sel_hi:[1,0]
	v_pk_mul_f32 v[40:41], v[40:41], v[186:187] op_sel_hi:[1,0]
	v_pk_mul_f32 v[38:39], v[38:39], v[186:187] op_sel_hi:[1,0]
	v_pk_mul_f32 v[36:37], v[36:37], v[186:187] op_sel_hi:[1,0]
	v_pk_mul_f32 v[34:35], v[34:35], v[186:187] op_sel_hi:[1,0]
	v_pk_mul_f32 v[32:33], v[32:33], v[186:187] op_sel_hi:[1,0]
	v_pk_mul_f32 v[30:31], v[30:31], v[186:187] op_sel_hi:[1,0]
	v_pk_mul_f32 v[28:29], v[28:29], v[186:187] op_sel_hi:[1,0]
	v_pk_mul_f32 v[26:27], v[26:27], v[186:187] op_sel_hi:[1,0]
	v_pk_mul_f32 v[24:25], v[24:25], v[186:187] op_sel_hi:[1,0]
	v_pk_mul_f32 v[22:23], v[22:23], v[186:187] op_sel_hi:[1,0]
	v_pk_mul_f32 v[20:21], v[20:21], v[186:187] op_sel_hi:[1,0]
	v_pk_mul_f32 v[18:19], v[18:19], v[186:187] op_sel_hi:[1,0]
	v_pk_mul_f32 v[16:17], v[16:17], v[186:187] op_sel_hi:[1,0]
	v_pk_mul_f32 v[14:15], v[14:15], v[186:187] op_sel_hi:[1,0]
	v_pk_mul_f32 v[12:13], v[12:13], v[186:187] op_sel_hi:[1,0]
	v_pk_mul_f32 v[10:11], v[10:11], v[186:187] op_sel_hi:[1,0]
	v_pk_mul_f32 v[8:9], v[8:9], v[186:187] op_sel_hi:[1,0]
	v_pk_mul_f32 v[6:7], v[6:7], v[186:187] op_sel_hi:[1,0]
	v_pk_mul_f32 v[4:5], v[4:5], v[186:187] op_sel_hi:[1,0]
	v_pk_mul_f32 v[2:3], v[2:3], v[186:187] op_sel_hi:[1,0]
	v_mul_f32_e32 v225, v225, v186
	v_add_f32_e32 v186, v187, v188
	v_sub_f32_e32 v82, v82, v186
	v_sub_f32_e32 v83, v83, v186
	v_sub_f32_e32 v84, v84, v186
	v_sub_f32_e32 v85, v85, v186
	v_sub_f32_e32 v86, v86, v186
	v_sub_f32_e32 v87, v87, v186
	v_sub_f32_e32 v88, v88, v186
	v_sub_f32_e32 v89, v89, v186
	v_sub_f32_e32 v90, v90, v186
	v_sub_f32_e32 v91, v91, v186
	v_sub_f32_e32 v92, v92, v186
	v_sub_f32_e32 v93, v93, v186
	v_sub_f32_e32 v94, v94, v186
	v_sub_f32_e32 v95, v95, v186
	v_sub_f32_e32 v96, v96, v186
	v_sub_f32_e32 v97, v97, v186
	v_sub_f32_e32 v66, v66, v186
	v_sub_f32_e32 v67, v67, v186
	v_sub_f32_e32 v68, v68, v186
	v_sub_f32_e32 v69, v69, v186
	v_sub_f32_e32 v70, v70, v186
	v_sub_f32_e32 v71, v71, v186
	v_sub_f32_e32 v72, v72, v186
	v_sub_f32_e32 v73, v73, v186
	v_sub_f32_e32 v74, v74, v186
	v_sub_f32_e32 v75, v75, v186
	v_sub_f32_e32 v76, v76, v186
	v_sub_f32_e32 v77, v77, v186
	v_sub_f32_e32 v78, v78, v186
	v_sub_f32_e32 v79, v79, v186
	v_sub_f32_e32 v80, v80, v186
	v_sub_f32_e32 v81, v81, v186
	v_sub_f32_e32 v188, 0, v187
	v_sub_f32_e32 v189, 0, v187
	v_sub_f32_e32 v190, 0, v187
	v_sub_f32_e32 v191, 0, v187
	v_sub_f32_e32 v192, 0, v187
	v_sub_f32_e32 v193, 0, v187
	v_sub_f32_e32 v194, 0, v187
	v_sub_f32_e32 v195, 0, v187
	v_sub_f32_e32 v196, 0, v187
	v_sub_f32_e32 v197, 0, v187
	v_sub_f32_e32 v198, 0, v187
	v_sub_f32_e32 v199, 0, v187
	v_sub_f32_e32 v200, 0, v187
	v_sub_f32_e32 v201, 0, v187
	v_sub_f32_e32 v202, 0, v187
	v_sub_f32_e32 v203, 0, v187
.Latt3_nr_10:
	v_exp_f32_e32 v82, v82
	v_exp_f32_e32 v83, v83
	v_exp_f32_e32 v84, v84
	v_exp_f32_e32 v85, v85
	v_exp_f32_e32 v86, v86
	v_exp_f32_e32 v87, v87
	v_exp_f32_e32 v88, v88
	v_exp_f32_e32 v89, v89
	v_cvt_pk_bf16_f32 v226, v82, v83
	v_cvt_pk_bf16_f32 v227, v84, v85
	v_cvt_pk_bf16_f32 v228, v86, v87
	v_cvt_pk_bf16_f32 v229, v88, v89
	s_nop 1
	s_waitcnt lgkmcnt(4)
	v_mfma_f32_32x32x16_bf16 v[50:65], v[236:239], v[226:229], v[50:65]
	ds_read_b128 v[236:239], v205 offset:30240
	v_exp_f32_e32 v90, v90
	v_exp_f32_e32 v91, v91
	v_exp_f32_e32 v92, v92
	v_exp_f32_e32 v93, v93
	s_waitcnt lgkmcnt(4)
	v_mfma_f32_32x32x16_bf16 v[34:49], v[240:243], v[226:229], v[34:49]
	ds_read_b128 v[240:243], v205 offset:34848
	v_exp_f32_e32 v94, v94
	v_exp_f32_e32 v95, v95
	v_exp_f32_e32 v96, v96
	v_exp_f32_e32 v97, v97
	s_waitcnt lgkmcnt(4)
	v_mfma_f32_32x32x16_bf16 v[18:33], v[244:247], v[226:229], v[18:33]
	ds_read_b128 v[244:247], v205 offset:39456
	v_add_f32_e32 v186, 0, v82
	v_add_f32_e32 v187, 0, v86
	v_add_f32_e32 v186, v83, v186
	v_add_f32_e32 v187, v87, v187
	s_waitcnt lgkmcnt(4)
	v_mfma_f32_32x32x16_bf16 v[2:17], v[248:251], v[226:229], v[2:17]
	ds_read_b128 v[248:251], v205 offset:25664
	v_add_f32_e32 v186, v84, v186
	v_add_f32_e32 v187, v88, v187
	v_add_f32_e32 v186, v85, v186
	v_add_f32_e32 v187, v89, v187
	v_cvt_pk_bf16_f32 v226, v90, v91
	v_cvt_pk_bf16_f32 v227, v92, v93
	v_cvt_pk_bf16_f32 v228, v94, v95
	v_cvt_pk_bf16_f32 v229, v96, v97
	s_nop 1
	s_waitcnt lgkmcnt(4)
	v_mfma_f32_32x32x16_bf16 v[50:65], v[210:213], v[226:229], v[50:65]
	ds_read_b128 v[210:213], v205 offset:30272
	v_exp_f32_e32 v66, v66
	v_exp_f32_e32 v67, v67
	v_exp_f32_e32 v68, v68
	v_exp_f32_e32 v69, v69
	s_waitcnt lgkmcnt(4)
	v_mfma_f32_32x32x16_bf16 v[34:49], v[236:239], v[226:229], v[34:49]
	ds_read_b128 v[236:239], v205 offset:34880
	v_exp_f32_e32 v70, v70
	v_exp_f32_e32 v71, v71
	v_exp_f32_e32 v72, v72
	v_exp_f32_e32 v73, v73
	s_waitcnt lgkmcnt(4)
	v_mfma_f32_32x32x16_bf16 v[18:33], v[240:243], v[226:229], v[18:33]
	ds_read_b128 v[240:243], v205 offset:39488
	v_add_f32_e32 v186, v90, v186
	v_add_f32_e32 v187, v94, v187
	v_add_f32_e32 v186, v91, v186
	v_add_f32_e32 v187, v95, v187
	s_waitcnt lgkmcnt(4)
	v_mfma_f32_32x32x16_bf16 v[2:17], v[244:247], v[226:229], v[2:17]
	ds_read_b128 v[244:247], v205 offset:25696
	v_add_f32_e32 v186, v92, v186
	v_add_f32_e32 v187, v96, v187
	v_add_f32_e32 v186, v93, v186
	v_add_f32_e32 v187, v97, v187
	v_cvt_pk_bf16_f32 v226, v66, v67
	v_cvt_pk_bf16_f32 v227, v68, v69
	v_cvt_pk_bf16_f32 v228, v70, v71
	v_cvt_pk_bf16_f32 v229, v72, v73
	s_nop 1
	s_waitcnt lgkmcnt(4)
	v_mfma_f32_32x32x16_bf16 v[50:65], v[248:251], v[226:229], v[50:65]
	ds_read_b128 v[248:251], v205 offset:30304
	v_exp_f32_e32 v74, v74
	v_exp_f32_e32 v75, v75
	v_exp_f32_e32 v76, v76
	v_exp_f32_e32 v77, v77
	s_waitcnt lgkmcnt(4)
	v_mfma_f32_32x32x16_bf16 v[34:49], v[210:213], v[226:229], v[34:49]
	ds_read_b128 v[210:213], v205 offset:34912
	v_exp_f32_e32 v78, v78
	v_exp_f32_e32 v79, v79
	v_exp_f32_e32 v80, v80
	v_exp_f32_e32 v81, v81
	s_waitcnt lgkmcnt(4)
	v_mfma_f32_32x32x16_bf16 v[18:33], v[236:239], v[226:229], v[18:33]
	ds_read_b128 v[236:239], v205 offset:39520
	v_add_f32_e32 v186, v66, v186
	v_add_f32_e32 v187, v70, v187
	v_add_f32_e32 v186, v67, v186
	v_add_f32_e32 v187, v71, v187
	s_waitcnt lgkmcnt(4)
	v_mfma_f32_32x32x16_bf16 v[2:17], v[240:243], v[226:229], v[2:17]
	v_add_f32_e32 v186, v68, v186
	v_add_f32_e32 v187, v72, v187
	v_add_f32_e32 v186, v69, v186
	v_add_f32_e32 v187, v73, v187
	v_cvt_pk_bf16_f32 v226, v74, v75
	v_cvt_pk_bf16_f32 v227, v76, v77
	v_cvt_pk_bf16_f32 v228, v78, v79
	v_cvt_pk_bf16_f32 v229, v80, v81
	s_nop 1
	s_waitcnt lgkmcnt(3)
	v_mfma_f32_32x32x16_bf16 v[50:65], v[244:247], v[226:229], v[50:65]
	v_add_f32_e32 v186, v74, v186
	v_add_f32_e32 v187, v78, v187
	s_waitcnt lgkmcnt(2)
	v_mfma_f32_32x32x16_bf16 v[34:49], v[248:251], v[226:229], v[34:49]
	v_add_f32_e32 v186, v75, v186
	v_add_f32_e32 v187, v79, v187
	s_waitcnt lgkmcnt(1)
	v_mfma_f32_32x32x16_bf16 v[18:33], v[210:213], v[226:229], v[18:33]
	v_add_f32_e32 v186, v76, v186
	v_add_f32_e32 v187, v80, v187
	s_waitcnt lgkmcnt(0)
	s_barrier
	v_mfma_f32_32x32x16_bf16 v[2:17], v[236:239], v[226:229], v[2:17]
	v_add_f32_e32 v186, v77, v186
	v_add_f32_e32 v187, v81, v187
	v_add_f32_e32 v186, v186, v187
	v_add_f32_e32 v224, v225, v186
	s_setprio 0
	s_add_i32 s13, s11, 2
	s_cmp_ge_u32 s13, s5
	s_cbranch_scc1 .Latt3_wskip_11
	v_add_u32_e32 v206, s72, v219
	v_add_u32_e32 v208, s72, v220
	v_add_u32_e32 v186, s72, v221
	v_add_u32_e32 v187, s72, v222
	s_add_i32 s13, s11, 3
	s_cmp_ge_u32 s13, s5
	s_cbranch_scc1 .Latt3_wtail_12
	s_waitcnt vmcnt(9)
	ds_write_b128 v206, v[102:105]
	s_waitcnt vmcnt(8)
	ds_write_b128 v208, v[106:109]
	s_waitcnt vmcnt(7)
	ds_write_b128 v186, v[114:117]
	s_waitcnt vmcnt(6)
	ds_write_b128 v187, v[98:101] offset:25600
	s_waitcnt vmcnt(5)
	ds_write_b128 v187, v[110:113] offset:34816
	s_branch .Latt3_wld_13

.Latt3_B_loop:
	v_add_u32_e32 v209, s70, v215
	v_add_u32_e32 v205, s70, v216
	ds_read_b128 v[226:229], v209
	ds_read_b128 v[236:239], v209 offset:12800
	ds_read_b128 v[240:243], v209 offset:32
	ds_read_b128 v[244:247], v209 offset:12832
	ds_read_b128 v[248:251], v209 offset:64
	ds_read_b128 v[210:213], v209 offset:12864
	s_waitcnt lgkmcnt(5)
	v_mfma_f32_32x32x16_bf16 v[82:97], v[226:229], v[126:129], v[188:203]
	ds_read_b128 v[226:229], v209 offset:96
	s_waitcnt lgkmcnt(5)
	v_mfma_f32_32x32x16_bf16 v[66:81], v[236:239], v[126:129], v[188:203]
	ds_read_b128 v[236:239], v209 offset:12896
	s_waitcnt lgkmcnt(5)
	v_mfma_f32_32x32x16_bf16 v[82:97], v[240:243], v[142:145], v[82:97]
	ds_read_b128 v[240:243], v209 offset:128
	s_waitcnt lgkmcnt(5)
	v_mfma_f32_32x32x16_bf16 v[66:81], v[244:247], v[142:145], v[66:81]
	ds_read_b128 v[244:247], v209 offset:12928
	s_waitcnt lgkmcnt(5)
	v_mfma_f32_32x32x16_bf16 v[82:97], v[248:251], v[146:149], v[82:97]
	ds_read_b128 v[248:251], v209 offset:160
	s_waitcnt lgkmcnt(5)
	v_mfma_f32_32x32x16_bf16 v[66:81], v[210:213], v[146:149], v[66:81]
	ds_read_b128 v[210:213], v209 offset:12960
	s_waitcnt lgkmcnt(5)
	v_mfma_f32_32x32x16_bf16 v[82:97], v[226:229], v[150:153], v[82:97]
	ds_read_b128 v[226:229], v209 offset:192
	s_waitcnt lgkmcnt(5)
	v_mfma_f32_32x32x16_bf16 v[66:81], v[236:239], v[150:153], v[66:81]
	ds_read_b128 v[236:239], v209 offset:12992
	s_waitcnt lgkmcnt(5)
	v_mfma_f32_32x32x16_bf16 v[82:97], v[240:243], v[154:157], v[82:97]
	ds_read_b128 v[240:243], v209 offset:224
	s_waitcnt lgkmcnt(5)
	v_mfma_f32_32x32x16_bf16 v[66:81], v[244:247], v[154:157], v[66:81]
	ds_read_b128 v[244:247], v209 offset:13024
	s_waitcnt lgkmcnt(5)
	v_mfma_f32_32x32x16_bf16 v[82:97], v[248:251], v[158:161], v[82:97]
	ds_read_b128 v[248:251], v209 offset:256
	s_waitcnt lgkmcnt(5)
	v_mfma_f32_32x32x16_bf16 v[66:81], v[210:213], v[158:161], v[66:81]
	ds_read_b128 v[210:213], v209 offset:13056
	s_waitcnt lgkmcnt(5)
	v_mfma_f32_32x32x16_bf16 v[82:97], v[226:229], v[162:165], v[82:97]
	ds_read_b128 v[226:229], v209 offset:288
	s_waitcnt lgkmcnt(5)
	v_mfma_f32_32x32x16_bf16 v[66:81], v[236:239], v[162:165], v[66:81]
	ds_read_b128 v[236:239], v209 offset:13088
	s_waitcnt lgkmcnt(5)
	v_mfma_f32_32x32x16_bf16 v[82:97], v[240:243], v[166:169], v[82:97]
	ds_read_b128 v[240:243], v209 offset:320
	s_waitcnt lgkmcnt(5)
	v_mfma_f32_32x32x16_bf16 v[66:81], v[244:247], v[166:169], v[66:81]
	ds_read_b128 v[244:247], v209 offset:13120
	s_waitcnt lgkmcnt(5)
	v_mfma_f32_32x32x16_bf16 v[82:97], v[248:251], v[170:173], v[82:97]
	ds_read_b128 v[248:251], v209 offset:352
	s_waitcnt lgkmcnt(5)
	v_mfma_f32_32x32x16_bf16 v[66:81], v[210:213], v[170:173], v[66:81]
	ds_read_b128 v[210:213], v209 offset:13152
	s_waitcnt lgkmcnt(5)
	v_mfma_f32_32x32x16_bf16 v[82:97], v[226:229], v[174:177], v[82:97]
	s_waitcnt lgkmcnt(4)
	v_mfma_f32_32x32x16_bf16 v[66:81], v[236:239], v[174:177], v[66:81]
	s_waitcnt lgkmcnt(3)
	v_mfma_f32_32x32x16_bf16 v[82:97], v[240:243], v[178:181], v[82:97]
	s_waitcnt lgkmcnt(2)
	v_mfma_f32_32x32x16_bf16 v[66:81], v[244:247], v[178:181], v[66:81]
	s_waitcnt lgkmcnt(1)
	v_mfma_f32_32x32x16_bf16 v[82:97], v[248:251], v[182:185], v[82:97]
	s_waitcnt lgkmcnt(0)
	s_barrier
	v_mfma_f32_32x32x16_bf16 v[66:81], v[210:213], v[182:185], v[66:81]
	s_setprio 2
	ds_read_b128 v[236:239], v205 offset:25600
	ds_read_b128 v[240:243], v205 offset:30208
	ds_read_b128 v[244:247], v205 offset:34816
	ds_read_b128 v[248:251], v205 offset:39424
	ds_read_b128 v[210:213], v205 offset:25632
	s_nop 4
	v_max_f32_e32 v186, v83, v83
	v_max_f32_e32 v187, v82, v82
	v_max_f32_e32 v186, v187, v186
	v_max3_f32 v186, v186, v84, v85
	v_max3_f32 v186, v186, v86, v87
	v_max3_f32 v186, v186, v88, v89
	v_max3_f32 v186, v186, v90, v91
	v_max3_f32 v186, v186, v92, v93
	v_max3_f32 v186, v186, v94, v95
	v_max3_f32 v186, v186, v96, v97
	v_max3_f32 v186, v186, v66, v67
	v_max3_f32 v186, v186, v68, v69
	v_max3_f32 v186, v186, v70, v71
	v_max3_f32 v186, v186, v72, v73
	v_max3_f32 v186, v186, v74, v75
	v_max3_f32 v186, v186, v76, v77
	v_max3_f32 v186, v186, v78, v79
	v_max3_f32 v186, v186, v80, v81
	v_mov_b32_e32 v187, v186
	s_nop 1
	v_permlane32_swap_b32_e32 v186, v187
	v_max_f32_e32 v187, v186, v187
	v_sub_f32_e32 v187, v187, v188
	v_add_f32_e32 v186, 0x41380000, v223
	v_cmp_gt_f32_e32 vcc, v187, v186
	s_cbranch_vccz .Latt3_nr_15
	v_max_f32_e32 v186, v187, v187
	v_max_f32_e32 v187, v223, v223
	v_max_f32_e32 v187, v187, v186
	v_sub_f32_e32 v186, v223, v187
	v_exp_f32_e32 v186, v186
	v_mov_b32_e32 v223, v187
	v_pk_mul_f32 v[64:65], v[64:65], v[186:187] op_sel_hi:[1,0]
	v_pk_mul_f32 v[62:63], v[62:63], v[186:187] op_sel_hi:[1,0]
	v_pk_mul_f32 v[60:61], v[60:61], v[186:187] op_sel_hi:[1,0]
	v_pk_mul_f32 v[58:59], v[58:59], v[186:187] op_sel_hi:[1,0]
	v_pk_mul_f32 v[56:57], v[56:57], v[186:187] op_sel_hi:[1,0]
	v_pk_mul_f32 v[54:55], v[54:55], v[186:187] op_sel_hi:[1,0]
	v_pk_mul_f32 v[52:53], v[52:53], v[186:187] op_sel_hi:[1,0]
	v_pk_mul_f32 v[50:51], v[50:51], v[186:187] op_sel_hi:[1,0]
	v_pk_mul_f32 v[48:49], v[48:49], v[186:187] op_sel_hi:[1,0]
	v_pk_mul_f32 v[46:47], v[46:47], v[186:187] op_sel_hi:[1,0]
	v_pk_mul_f32 v[44:45], v[44:45], v[186:187] op_sel_hi:[1,0]
	v_pk_mul_f32 v[42:43], v[42:43], v[186:187] op_sel_hi:[1,0]
	v_pk_mul_f32 v[40:41], v[40:41], v[186:187] op_sel_hi:[1,0]
	v_pk_mul_f32 v[38:39], v[38:39], v[186:187] op_sel_hi:[1,0]
	v_pk_mul_f32 v[36:37], v[36:37], v[186:187] op_sel_hi:[1,0]
	v_pk_mul_f32 v[34:35], v[34:35], v[186:187] op_sel_hi:[1,0]
	v_pk_mul_f32 v[32:33], v[32:33], v[186:187] op_sel_hi:[1,0]
	v_pk_mul_f32 v[30:31], v[30:31], v[186:187] op_sel_hi:[1,0]
	v_pk_mul_f32 v[28:29], v[28:29], v[186:187] op_sel_hi:[1,0]
	v_pk_mul_f32 v[26:27], v[26:27], v[186:187] op_sel_hi:[1,0]
	v_pk_mul_f32 v[24:25], v[24:25], v[186:187] op_sel_hi:[1,0]
	v_pk_mul_f32 v[22:23], v[22:23], v[186:187] op_sel_hi:[1,0]
	v_pk_mul_f32 v[20:21], v[20:21], v[186:187] op_sel_hi:[1,0]
	v_pk_mul_f32 v[18:19], v[18:19], v[186:187] op_sel_hi:[1,0]
	v_pk_mul_f32 v[16:17], v[16:17], v[186:187] op_sel_hi:[1,0]
	v_pk_mul_f32 v[14:15], v[14:15], v[186:187] op_sel_hi:[1,0]
	v_pk_mul_f32 v[12:13], v[12:13], v[186:187] op_sel_hi:[1,0]
	v_pk_mul_f32 v[10:11], v[10:11], v[186:187] op_sel_hi:[1,0]
	v_pk_mul_f32 v[8:9], v[8:9], v[186:187] op_sel_hi:[1,0]
	v_pk_mul_f32 v[6:7], v[6:7], v[186:187] op_sel_hi:[1,0]
	v_pk_mul_f32 v[4:5], v[4:5], v[186:187] op_sel_hi:[1,0]
	v_pk_mul_f32 v[2:3], v[2:3], v[186:187] op_sel_hi:[1,0]
	v_mul_f32_e32 v224, v224, v186
	v_add_f32_e32 v186, v187, v188
	v_sub_f32_e32 v82, v82, v186
	v_sub_f32_e32 v83, v83, v186
	v_sub_f32_e32 v84, v84, v186
	v_sub_f32_e32 v85, v85, v186
	v_sub_f32_e32 v86, v86, v186
	v_sub_f32_e32 v87, v87, v186
	v_sub_f32_e32 v88, v88, v186
	v_sub_f32_e32 v89, v89, v186
	v_sub_f32_e32 v90, v90, v186
	v_sub_f32_e32 v91, v91, v186
	v_sub_f32_e32 v92, v92, v186
	v_sub_f32_e32 v93, v93, v186
	v_sub_f32_e32 v94, v94, v186
	v_sub_f32_e32 v95, v95, v186
	v_sub_f32_e32 v96, v96, v186
	v_sub_f32_e32 v97, v97, v186
	v_sub_f32_e32 v66, v66, v186
	v_sub_f32_e32 v67, v67, v186
	v_sub_f32_e32 v68, v68, v186
	v_sub_f32_e32 v69, v69, v186
	v_sub_f32_e32 v70, v70, v186
	v_sub_f32_e32 v71, v71, v186
	v_sub_f32_e32 v72, v72, v186
	v_sub_f32_e32 v73, v73, v186
	v_sub_f32_e32 v74, v74, v186
	v_sub_f32_e32 v75, v75, v186
	v_sub_f32_e32 v76, v76, v186
	v_sub_f32_e32 v77, v77, v186
	v_sub_f32_e32 v78, v78, v186
	v_sub_f32_e32 v79, v79, v186
	v_sub_f32_e32 v80, v80, v186
	v_sub_f32_e32 v81, v81, v186
	v_sub_f32_e32 v188, 0, v187
	v_sub_f32_e32 v189, 0, v187
	v_sub_f32_e32 v190, 0, v187
	v_sub_f32_e32 v191, 0, v187
	v_sub_f32_e32 v192, 0, v187
	v_sub_f32_e32 v193, 0, v187
	v_sub_f32_e32 v194, 0, v187
	v_sub_f32_e32 v195, 0, v187
	v_sub_f32_e32 v196, 0, v187
	v_sub_f32_e32 v197, 0, v187
	v_sub_f32_e32 v198, 0, v187
	v_sub_f32_e32 v199, 0, v187
	v_sub_f32_e32 v200, 0, v187
	v_sub_f32_e32 v201, 0, v187
	v_sub_f32_e32 v202, 0, v187
	v_sub_f32_e32 v203, 0, v187
.Latt3_nr_15:
	v_exp_f32_e32 v82, v82
	v_exp_f32_e32 v83, v83
	v_exp_f32_e32 v84, v84
	v_exp_f32_e32 v85, v85
	v_exp_f32_e32 v86, v86
	v_exp_f32_e32 v87, v87
	v_exp_f32_e32 v88, v88
	v_exp_f32_e32 v89, v89
	v_cvt_pk_bf16_f32 v226, v82, v83
	v_cvt_pk_bf16_f32 v227, v84, v85
	v_cvt_pk_bf16_f32 v228, v86, v87
	v_cvt_pk_bf16_f32 v229, v88, v89
	s_nop 1
	s_waitcnt lgkmcnt(4)
	v_mfma_f32_32x32x16_bf16 v[50:65], v[236:239], v[226:229], v[50:65]
	ds_read_b128 v[236:239], v205 offset:30240
	v_exp_f32_e32 v90, v90
	v_exp_f32_e32 v91, v91
	v_exp_f32_e32 v92, v92
	v_exp_f32_e32 v93, v93
	s_waitcnt lgkmcnt(4)
	v_mfma_f32_32x32x16_bf16 v[34:49], v[240:243], v[226:229], v[34:49]
	ds_read_b128 v[240:243], v205 offset:34848
	v_exp_f32_e32 v94, v94
	v_exp_f32_e32 v95, v95
	v_exp_f32_e32 v96, v96
	v_exp_f32_e32 v97, v97
	s_waitcnt lgkmcnt(4)
	v_mfma_f32_32x32x16_bf16 v[18:33], v[244:247], v[226:229], v[18:33]
	ds_read_b128 v[244:247], v205 offset:39456
	v_add_f32_e32 v186, 0, v82
	v_add_f32_e32 v187, 0, v86
	v_add_f32_e32 v186, v83, v186
	v_add_f32_e32 v187, v87, v187
	s_waitcnt lgkmcnt(4)
	v_mfma_f32_32x32x16_bf16 v[2:17], v[248:251], v[226:229], v[2:17]
	ds_read_b128 v[248:251], v205 offset:25664
	v_add_f32_e32 v186, v84, v186
	v_add_f32_e32 v187, v88, v187
	v_add_f32_e32 v186, v85, v186
	v_add_f32_e32 v187, v89, v187
	v_cvt_pk_bf16_f32 v226, v90, v91
	v_cvt_pk_bf16_f32 v227, v92, v93
	v_cvt_pk_bf16_f32 v228, v94, v95
	v_cvt_pk_bf16_f32 v229, v96, v97
	s_nop 1
	s_waitcnt lgkmcnt(4)
	v_mfma_f32_32x32x16_bf16 v[50:65], v[210:213], v[226:229], v[50:65]
	ds_read_b128 v[210:213], v205 offset:30272
	v_exp_f32_e32 v66, v66
	v_exp_f32_e32 v67, v67
	v_exp_f32_e32 v68, v68
	v_exp_f32_e32 v69, v69
	s_waitcnt lgkmcnt(4)
	v_mfma_f32_32x32x16_bf16 v[34:49], v[236:239], v[226:229], v[34:49]
	ds_read_b128 v[236:239], v205 offset:34880
	v_exp_f32_e32 v70, v70
	v_exp_f32_e32 v71, v71
	v_exp_f32_e32 v72, v72
	v_exp_f32_e32 v73, v73
	s_waitcnt lgkmcnt(4)
	v_mfma_f32_32x32x16_bf16 v[18:33], v[240:243], v[226:229], v[18:33]
	ds_read_b128 v[240:243], v205 offset:39488
	v_add_f32_e32 v186, v90, v186
	v_add_f32_e32 v187, v94, v187
	v_add_f32_e32 v186, v91, v186
	v_add_f32_e32 v187, v95, v187
	s_waitcnt lgkmcnt(4)
	v_mfma_f32_32x32x16_bf16 v[2:17], v[244:247], v[226:229], v[2:17]
	ds_read_b128 v[244:247], v205 offset:25696
	v_add_f32_e32 v186, v92, v186
	v_add_f32_e32 v187, v96, v187
	v_add_f32_e32 v186, v93, v186
	v_add_f32_e32 v187, v97, v187
	v_cvt_pk_bf16_f32 v226, v66, v67
	v_cvt_pk_bf16_f32 v227, v68, v69
	v_cvt_pk_bf16_f32 v228, v70, v71
	v_cvt_pk_bf16_f32 v229, v72, v73
	s_nop 1
	s_waitcnt lgkmcnt(4)
	v_mfma_f32_32x32x16_bf16 v[50:65], v[248:251], v[226:229], v[50:65]
	ds_read_b128 v[248:251], v205 offset:30304
	v_exp_f32_e32 v74, v74
	v_exp_f32_e32 v75, v75
	v_exp_f32_e32 v76, v76
	v_exp_f32_e32 v77, v77
	s_waitcnt lgkmcnt(4)
	v_mfma_f32_32x32x16_bf16 v[34:49], v[210:213], v[226:229], v[34:49]
	ds_read_b128 v[210:213], v205 offset:34912
	v_exp_f32_e32 v78, v78
	v_exp_f32_e32 v79, v79
	v_exp_f32_e32 v80, v80
	v_exp_f32_e32 v81, v81
	s_waitcnt lgkmcnt(4)
	v_mfma_f32_32x32x16_bf16 v[18:33], v[236:239], v[226:229], v[18:33]
	ds_read_b128 v[236:239], v205 offset:39520
	v_add_f32_e32 v186, v66, v186
	v_add_f32_e32 v187, v70, v187
	v_add_f32_e32 v186, v67, v186
	v_add_f32_e32 v187, v71, v187
	s_waitcnt lgkmcnt(4)
	v_mfma_f32_32x32x16_bf16 v[2:17], v[240:243], v[226:229], v[2:17]
	v_add_f32_e32 v186, v68, v186
	v_add_f32_e32 v187, v72, v187
	v_add_f32_e32 v186, v69, v186
	v_add_f32_e32 v187, v73, v187
	v_cvt_pk_bf16_f32 v226, v74, v75
	v_cvt_pk_bf16_f32 v227, v76, v77
	v_cvt_pk_bf16_f32 v228, v78, v79
	v_cvt_pk_bf16_f32 v229, v80, v81
	s_nop 1
	s_waitcnt lgkmcnt(3)
	v_mfma_f32_32x32x16_bf16 v[50:65], v[244:247], v[226:229], v[50:65]
	v_add_f32_e32 v186, v74, v186
	v_add_f32_e32 v187, v78, v187
	s_waitcnt lgkmcnt(2)
	v_mfma_f32_32x32x16_bf16 v[34:49], v[248:251], v[226:229], v[34:49]
	v_add_f32_e32 v186, v75, v186
	v_add_f32_e32 v187, v79, v187
	s_waitcnt lgkmcnt(1)
	v_mfma_f32_32x32x16_bf16 v[18:33], v[210:213], v[226:229], v[18:33]
	v_add_f32_e32 v186, v76, v186
	v_add_f32_e32 v187, v80, v187
	s_waitcnt lgkmcnt(0)
	v_mfma_f32_32x32x16_bf16 v[2:17], v[236:239], v[226:229], v[2:17]
	v_add_f32_e32 v186, v77, v186
	v_add_f32_e32 v187, v81, v187
	v_add_f32_e32 v186, v186, v187
	v_add_f32_e32 v225, v224, v186
	s_setprio 0
	s_add_i32 s13, s11, 2
	s_cmp_ge_u32 s13, s5
	s_cbranch_scc1 .Latt3_wskip_16
	v_add_u32_e32 v206, s72, v219
	v_add_u32_e32 v208, s72, v220
	v_add_u32_e32 v186, s72, v221
	v_add_u32_e32 v187, s72, v222
	s_add_i32 s13, s11, 3
	s_cmp_ge_u32 s13, s5
	s_cbranch_scc1 .Latt3_wtail_17
	s_waitcnt vmcnt(9)
	ds_write_b128 v206, v[118:121]
	s_waitcnt vmcnt(8)
	ds_write_b128 v208, v[122:125]
	s_waitcnt vmcnt(7)
	ds_write_b128 v186, v[130:133]
	s_waitcnt vmcnt(6)
	ds_write_b128 v187, v[134:137] offset:25600
	s_waitcnt vmcnt(5)
	ds_write_b128 v187, v[138:141] offset:34816
	s_branch .Latt3_wld_18

.Latt3_wdone_19:
.Latt3_wskip_16:
	s_mov_b32 s13, s70
	s_mov_b32 s70, s71
	s_mov_b32 s71, s72
	s_mov_b32 s72, s13
	s_add_i32 s11, s11, 1
	v_add_u32_e32 v209, s70, v215
	v_add_u32_e32 v205, s70, v216
	ds_read_b128 v[226:229], v209
	ds_read_b128 v[236:239], v209 offset:12800
	ds_read_b128 v[240:243], v209 offset:32
	ds_read_b128 v[244:247], v209 offset:12832
	ds_read_b128 v[248:251], v209 offset:64
	ds_read_b128 v[210:213], v209 offset:12864
	s_waitcnt lgkmcnt(5)
	v_mfma_f32_32x32x16_bf16 v[82:97], v[226:229], v[126:129], v[188:203]
	ds_read_b128 v[226:229], v209 offset:96
	s_waitcnt lgkmcnt(5)
	v_mfma_f32_32x32x16_bf16 v[66:81], v[236:239], v[126:129], v[188:203]
	ds_read_b128 v[236:239], v209 offset:12896
	s_waitcnt lgkmcnt(5)
	v_mfma_f32_32x32x16_bf16 v[82:97], v[240:243], v[142:145], v[82:97]
	ds_read_b128 v[240:243], v209 offset:128
	s_waitcnt lgkmcnt(5)
	v_mfma_f32_32x32x16_bf16 v[66:81], v[244:247], v[142:145], v[66:81]
	ds_read_b128 v[244:247], v209 offset:12928
	s_waitcnt lgkmcnt(5)
	v_mfma_f32_32x32x16_bf16 v[82:97], v[248:251], v[146:149], v[82:97]
	ds_read_b128 v[248:251], v209 offset:160
	s_waitcnt lgkmcnt(5)
	v_mfma_f32_32x32x16_bf16 v[66:81], v[210:213], v[146:149], v[66:81]
	ds_read_b128 v[210:213], v209 offset:12960
	s_waitcnt lgkmcnt(5)
	v_mfma_f32_32x32x16_bf16 v[82:97], v[226:229], v[150:153], v[82:97]
	ds_read_b128 v[226:229], v209 offset:192
	s_waitcnt lgkmcnt(5)
	v_mfma_f32_32x32x16_bf16 v[66:81], v[236:239], v[150:153], v[66:81]
	ds_read_b128 v[236:239], v209 offset:12992
	s_waitcnt lgkmcnt(5)
	v_mfma_f32_32x32x16_bf16 v[82:97], v[240:243], v[154:157], v[82:97]
	ds_read_b128 v[240:243], v209 offset:224
	s_waitcnt lgkmcnt(5)
	v_mfma_f32_32x32x16_bf16 v[66:81], v[244:247], v[154:157], v[66:81]
	ds_read_b128 v[244:247], v209 offset:13024
	s_waitcnt lgkmcnt(5)
	v_mfma_f32_32x32x16_bf16 v[82:97], v[248:251], v[158:161], v[82:97]
	ds_read_b128 v[248:251], v209 offset:256
	s_waitcnt lgkmcnt(5)
	v_mfma_f32_32x32x16_bf16 v[66:81], v[210:213], v[158:161], v[66:81]
	ds_read_b128 v[210:213], v209 offset:13056
	s_waitcnt lgkmcnt(5)
	v_mfma_f32_32x32x16_bf16 v[82:97], v[226:229], v[162:165], v[82:97]
	ds_read_b128 v[226:229], v209 offset:288
	s_waitcnt lgkmcnt(5)
	v_mfma_f32_32x32x16_bf16 v[66:81], v[236:239], v[162:165], v[66:81]
	ds_read_b128 v[236:239], v209 offset:13088
	s_waitcnt lgkmcnt(5)
	v_mfma_f32_32x32x16_bf16 v[82:97], v[240:243], v[166:169], v[82:97]
	ds_read_b128 v[240:243], v209 offset:320
	s_waitcnt lgkmcnt(5)
	v_mfma_f32_32x32x16_bf16 v[66:81], v[244:247], v[166:169], v[66:81]
	ds_read_b128 v[244:247], v209 offset:13120
	s_waitcnt lgkmcnt(5)
	v_mfma_f32_32x32x16_bf16 v[82:97], v[248:251], v[170:173], v[82:97]
	ds_read_b128 v[248:251], v209 offset:352
	s_waitcnt lgkmcnt(5)
	v_mfma_f32_32x32x16_bf16 v[66:81], v[210:213], v[170:173], v[66:81]
	ds_read_b128 v[210:213], v209 offset:13152
	s_waitcnt lgkmcnt(5)
	v_mfma_f32_32x32x16_bf16 v[82:97], v[226:229], v[174:177], v[82:97]
	s_waitcnt lgkmcnt(4)
	v_mfma_f32_32x32x16_bf16 v[66:81], v[236:239], v[174:177], v[66:81]
	s_waitcnt lgkmcnt(3)
	v_mfma_f32_32x32x16_bf16 v[82:97], v[240:243], v[178:181], v[82:97]
	s_waitcnt lgkmcnt(2)
	v_mfma_f32_32x32x16_bf16 v[66:81], v[244:247], v[178:181], v[66:81]
	s_waitcnt lgkmcnt(1)
	v_mfma_f32_32x32x16_bf16 v[82:97], v[248:251], v[182:185], v[82:97]
	s_waitcnt lgkmcnt(0)
	s_barrier
	v_mfma_f32_32x32x16_bf16 v[66:81], v[210:213], v[182:185], v[66:81]
	s_setprio 2
	ds_read_b128 v[236:239], v205 offset:25600
	ds_read_b128 v[240:243], v205 offset:30208
	ds_read_b128 v[244:247], v205 offset:34816
	ds_read_b128 v[248:251], v205 offset:39424
	ds_read_b128 v[210:213], v205 offset:25632
	s_nop 4
	v_max_f32_e32 v186, v83, v83
	v_max_f32_e32 v187, v82, v82
	v_max_f32_e32 v186, v187, v186
	v_max3_f32 v186, v186, v84, v85
	v_max3_f32 v186, v186, v86, v87
	v_max3_f32 v186, v186, v88, v89
	v_max3_f32 v186, v186, v90, v91
	v_max3_f32 v186, v186, v92, v93
	v_max3_f32 v186, v186, v94, v95
	v_max3_f32 v186, v186, v96, v97
	v_max3_f32 v186, v186, v66, v67
	v_max3_f32 v186, v186, v68, v69
	v_max3_f32 v186, v186, v70, v71
	v_max3_f32 v186, v186, v72, v73
	v_max3_f32 v186, v186, v74, v75
	v_max3_f32 v186, v186, v76, v77
	v_max3_f32 v186, v186, v78, v79
	v_max3_f32 v186, v186, v80, v81
	v_mov_b32_e32 v187, v186
	s_nop 1
	v_permlane32_swap_b32_e32 v186, v187
	v_max_f32_e32 v187, v186, v187
	v_sub_f32_e32 v187, v187, v188
	v_add_f32_e32 v186, 0x41380000, v223
	v_cmp_gt_f32_e32 vcc, v187, v186
	s_cbranch_vccz .Latt3_nr_20
	v_max_f32_e32 v186, v187, v187
	v_max_f32_e32 v187, v223, v223
	v_max_f32_e32 v187, v187, v186
	v_sub_f32_e32 v186, v223, v187
	v_exp_f32_e32 v186, v186
	v_mov_b32_e32 v223, v187
	v_pk_mul_f32 v[64:65], v[64:65], v[186:187] op_sel_hi:[1,0]
	v_pk_mul_f32 v[62:63], v[62:63], v[186:187] op_sel_hi:[1,0]
	v_pk_mul_f32 v[60:61], v[60:61], v[186:187] op_sel_hi:[1,0]
	v_pk_mul_f32 v[58:59], v[58:59], v[186:187] op_sel_hi:[1,0]
	v_pk_mul_f32 v[56:57], v[56:57], v[186:187] op_sel_hi:[1,0]
	v_pk_mul_f32 v[54:55], v[54:55], v[186:187] op_sel_hi:[1,0]
	v_pk_mul_f32 v[52:53], v[52:53], v[186:187] op_sel_hi:[1,0]
	v_pk_mul_f32 v[50:51], v[50:51], v[186:187] op_sel_hi:[1,0]
	v_pk_mul_f32 v[48:49], v[48:49], v[186:187] op_sel_hi:[1,0]
	v_pk_mul_f32 v[46:47], v[46:47], v[186:187] op_sel_hi:[1,0]
	v_pk_mul_f32 v[44:45], v[44:45], v[186:187] op_sel_hi:[1,0]
	v_pk_mul_f32 v[42:43], v[42:43], v[186:187] op_sel_hi:[1,0]
	v_pk_mul_f32 v[40:41], v[40:41], v[186:187] op_sel_hi:[1,0]
	v_pk_mul_f32 v[38:39], v[38:39], v[186:187] op_sel_hi:[1,0]
	v_pk_mul_f32 v[36:37], v[36:37], v[186:187] op_sel_hi:[1,0]
	v_pk_mul_f32 v[34:35], v[34:35], v[186:187] op_sel_hi:[1,0]
	v_pk_mul_f32 v[32:33], v[32:33], v[186:187] op_sel_hi:[1,0]
	v_pk_mul_f32 v[30:31], v[30:31], v[186:187] op_sel_hi:[1,0]
	v_pk_mul_f32 v[28:29], v[28:29], v[186:187] op_sel_hi:[1,0]
	v_pk_mul_f32 v[26:27], v[26:27], v[186:187] op_sel_hi:[1,0]
	v_pk_mul_f32 v[24:25], v[24:25], v[186:187] op_sel_hi:[1,0]
	v_pk_mul_f32 v[22:23], v[22:23], v[186:187] op_sel_hi:[1,0]
	v_pk_mul_f32 v[20:21], v[20:21], v[186:187] op_sel_hi:[1,0]
	v_pk_mul_f32 v[18:19], v[18:19], v[186:187] op_sel_hi:[1,0]
	v_pk_mul_f32 v[16:17], v[16:17], v[186:187] op_sel_hi:[1,0]
	v_pk_mul_f32 v[14:15], v[14:15], v[186:187] op_sel_hi:[1,0]
	v_pk_mul_f32 v[12:13], v[12:13], v[186:187] op_sel_hi:[1,0]
	v_pk_mul_f32 v[10:11], v[10:11], v[186:187] op_sel_hi:[1,0]
	v_pk_mul_f32 v[8:9], v[8:9], v[186:187] op_sel_hi:[1,0]
	v_pk_mul_f32 v[6:7], v[6:7], v[186:187] op_sel_hi:[1,0]
	v_pk_mul_f32 v[4:5], v[4:5], v[186:187] op_sel_hi:[1,0]
	v_pk_mul_f32 v[2:3], v[2:3], v[186:187] op_sel_hi:[1,0]
	v_mul_f32_e32 v225, v225, v186
	v_add_f32_e32 v186, v187, v188
	v_sub_f32_e32 v82, v82, v186
	v_sub_f32_e32 v83, v83, v186
	v_sub_f32_e32 v84, v84, v186
	v_sub_f32_e32 v85, v85, v186
	v_sub_f32_e32 v86, v86, v186
	v_sub_f32_e32 v87, v87, v186
	v_sub_f32_e32 v88, v88, v186
	v_sub_f32_e32 v89, v89, v186
	v_sub_f32_e32 v90, v90, v186
	v_sub_f32_e32 v91, v91, v186
	v_sub_f32_e32 v92, v92, v186
	v_sub_f32_e32 v93, v93, v186
	v_sub_f32_e32 v94, v94, v186
	v_sub_f32_e32 v95, v95, v186
	v_sub_f32_e32 v96, v96, v186
	v_sub_f32_e32 v97, v97, v186
	v_sub_f32_e32 v66, v66, v186
	v_sub_f32_e32 v67, v67, v186
	v_sub_f32_e32 v68, v68, v186
	v_sub_f32_e32 v69, v69, v186
	v_sub_f32_e32 v70, v70, v186
	v_sub_f32_e32 v71, v71, v186
	v_sub_f32_e32 v72, v72, v186
	v_sub_f32_e32 v73, v73, v186
	v_sub_f32_e32 v74, v74, v186
	v_sub_f32_e32 v75, v75, v186
	v_sub_f32_e32 v76, v76, v186
	v_sub_f32_e32 v77, v77, v186
	v_sub_f32_e32 v78, v78, v186
	v_sub_f32_e32 v79, v79, v186
	v_sub_f32_e32 v80, v80, v186
	v_sub_f32_e32 v81, v81, v186
	v_sub_f32_e32 v188, 0, v187
	v_sub_f32_e32 v189, 0, v187
	v_sub_f32_e32 v190, 0, v187
	v_sub_f32_e32 v191, 0, v187
	v_sub_f32_e32 v192, 0, v187
	v_sub_f32_e32 v193, 0, v187
	v_sub_f32_e32 v194, 0, v187
	v_sub_f32_e32 v195, 0, v187
	v_sub_f32_e32 v196, 0, v187
	v_sub_f32_e32 v197, 0, v187
	v_sub_f32_e32 v198, 0, v187
	v_sub_f32_e32 v199, 0, v187
	v_sub_f32_e32 v200, 0, v187
	v_sub_f32_e32 v201, 0, v187
	v_sub_f32_e32 v202, 0, v187
	v_sub_f32_e32 v203, 0, v187
.Latt3_nr_20:
	v_exp_f32_e32 v82, v82
	v_exp_f32_e32 v83, v83
	v_exp_f32_e32 v84, v84
	v_exp_f32_e32 v85, v85
	v_exp_f32_e32 v86, v86
	v_exp_f32_e32 v87, v87
	v_exp_f32_e32 v88, v88
	v_exp_f32_e32 v89, v89
	v_cvt_pk_bf16_f32 v226, v82, v83
	v_cvt_pk_bf16_f32 v227, v84, v85
	v_cvt_pk_bf16_f32 v228, v86, v87
	v_cvt_pk_bf16_f32 v229, v88, v89
	s_nop 1
	s_waitcnt lgkmcnt(4)
	v_mfma_f32_32x32x16_bf16 v[50:65], v[236:239], v[226:229], v[50:65]
	ds_read_b128 v[236:239], v205 offset:30240
	v_exp_f32_e32 v90, v90
	v_exp_f32_e32 v91, v91
	v_exp_f32_e32 v92, v92
	v_exp_f32_e32 v93, v93
	s_waitcnt lgkmcnt(4)
	v_mfma_f32_32x32x16_bf16 v[34:49], v[240:243], v[226:229], v[34:49]
	ds_read_b128 v[240:243], v205 offset:34848
	v_exp_f32_e32 v94, v94
	v_exp_f32_e32 v95, v95
	v_exp_f32_e32 v96, v96
	v_exp_f32_e32 v97, v97
	s_waitcnt lgkmcnt(4)
	v_mfma_f32_32x32x16_bf16 v[18:33], v[244:247], v[226:229], v[18:33]
	ds_read_b128 v[244:247], v205 offset:39456
	v_add_f32_e32 v186, 0, v82
	v_add_f32_e32 v187, 0, v86
	v_add_f32_e32 v186, v83, v186
	v_add_f32_e32 v187, v87, v187
	s_waitcnt lgkmcnt(4)
	v_mfma_f32_32x32x16_bf16 v[2:17], v[248:251], v[226:229], v[2:17]
	ds_read_b128 v[248:251], v205 offset:25664
	v_add_f32_e32 v186, v84, v186
	v_add_f32_e32 v187, v88, v187
	v_add_f32_e32 v186, v85, v186
	v_add_f32_e32 v187, v89, v187
	v_cvt_pk_bf16_f32 v226, v90, v91
	v_cvt_pk_bf16_f32 v227, v92, v93
	v_cvt_pk_bf16_f32 v228, v94, v95
	v_cvt_pk_bf16_f32 v229, v96, v97
	s_nop 1
	s_waitcnt lgkmcnt(4)
	v_mfma_f32_32x32x16_bf16 v[50:65], v[210:213], v[226:229], v[50:65]
	ds_read_b128 v[210:213], v205 offset:30272
	v_exp_f32_e32 v66, v66
	v_exp_f32_e32 v67, v67
	v_exp_f32_e32 v68, v68
	v_exp_f32_e32 v69, v69
	s_waitcnt lgkmcnt(4)
	v_mfma_f32_32x32x16_bf16 v[34:49], v[236:239], v[226:229], v[34:49]
	ds_read_b128 v[236:239], v205 offset:34880
	v_exp_f32_e32 v70, v70
	v_exp_f32_e32 v71, v71
	v_exp_f32_e32 v72, v72
	v_exp_f32_e32 v73, v73
	s_waitcnt lgkmcnt(4)
	v_mfma_f32_32x32x16_bf16 v[18:33], v[240:243], v[226:229], v[18:33]
	ds_read_b128 v[240:243], v205 offset:39488
	v_add_f32_e32 v186, v90, v186
	v_add_f32_e32 v187, v94, v187
	v_add_f32_e32 v186, v91, v186
	v_add_f32_e32 v187, v95, v187
	s_waitcnt lgkmcnt(4)
	v_mfma_f32_32x32x16_bf16 v[2:17], v[244:247], v[226:229], v[2:17]
	ds_read_b128 v[244:247], v205 offset:25696
	v_add_f32_e32 v186, v92, v186
	v_add_f32_e32 v187, v96, v187
	v_add_f32_e32 v186, v93, v186
	v_add_f32_e32 v187, v97, v187
	v_cvt_pk_bf16_f32 v226, v66, v67
	v_cvt_pk_bf16_f32 v227, v68, v69
	v_cvt_pk_bf16_f32 v228, v70, v71
	v_cvt_pk_bf16_f32 v229, v72, v73
	s_nop 1
	s_waitcnt lgkmcnt(4)
	v_mfma_f32_32x32x16_bf16 v[50:65], v[248:251], v[226:229], v[50:65]
	ds_read_b128 v[248:251], v205 offset:30304
	v_exp_f32_e32 v74, v74
	v_exp_f32_e32 v75, v75
	v_exp_f32_e32 v76, v76
	v_exp_f32_e32 v77, v77
	s_waitcnt lgkmcnt(4)
	v_mfma_f32_32x32x16_bf16 v[34:49], v[210:213], v[226:229], v[34:49]
	ds_read_b128 v[210:213], v205 offset:34912
	v_exp_f32_e32 v78, v78
	v_exp_f32_e32 v79, v79
	v_exp_f32_e32 v80, v80
	v_exp_f32_e32 v81, v81
	s_waitcnt lgkmcnt(4)
	v_mfma_f32_32x32x16_bf16 v[18:33], v[236:239], v[226:229], v[18:33]
	ds_read_b128 v[236:239], v205 offset:39520
	v_add_f32_e32 v186, v66, v186
	v_add_f32_e32 v187, v70, v187
	v_add_f32_e32 v186, v67, v186
	v_add_f32_e32 v187, v71, v187
	s_waitcnt lgkmcnt(4)
	v_mfma_f32_32x32x16_bf16 v[2:17], v[240:243], v[226:229], v[2:17]
	v_add_f32_e32 v186, v68, v186
	v_add_f32_e32 v187, v72, v187
	v_add_f32_e32 v186, v69, v186
	v_add_f32_e32 v187, v73, v187
	v_cvt_pk_bf16_f32 v226, v74, v75
	v_cvt_pk_bf16_f32 v227, v76, v77
	v_cvt_pk_bf16_f32 v228, v78, v79
	v_cvt_pk_bf16_f32 v229, v80, v81
	s_nop 1
	s_waitcnt lgkmcnt(3)
	v_mfma_f32_32x32x16_bf16 v[50:65], v[244:247], v[226:229], v[50:65]
	v_add_f32_e32 v186, v74, v186
	v_add_f32_e32 v187, v78, v187
	s_waitcnt lgkmcnt(2)
	v_mfma_f32_32x32x16_bf16 v[34:49], v[248:251], v[226:229], v[34:49]
	v_add_f32_e32 v186, v75, v186
	v_add_f32_e32 v187, v79, v187
	s_waitcnt lgkmcnt(1)
	v_mfma_f32_32x32x16_bf16 v[18:33], v[210:213], v[226:229], v[18:33]
	v_add_f32_e32 v186, v76, v186
	v_add_f32_e32 v187, v80, v187
	s_waitcnt lgkmcnt(0)
	v_mfma_f32_32x32x16_bf16 v[2:17], v[236:239], v[226:229], v[2:17]
	v_add_f32_e32 v186, v77, v186
	v_add_f32_e32 v187, v81, v187
	v_add_f32_e32 v186, v186, v187
	v_add_f32_e32 v224, v225, v186
	s_setprio 0
	s_add_i32 s13, s11, 2
	s_cmp_ge_u32 s13, s5
	s_cbranch_scc1 .Latt3_wskip_21
	v_add_u32_e32 v206, s72, v219
	v_add_u32_e32 v208, s72, v220
	v_add_u32_e32 v186, s72, v221
	v_add_u32_e32 v187, s72, v222
	s_add_i32 s13, s11, 3
	s_cmp_ge_u32 s13, s5
	s_cbranch_scc1 .Latt3_wtail_22
	s_waitcnt vmcnt(9)
	ds_write_b128 v206, v[102:105]
	s_waitcnt vmcnt(8)
	ds_write_b128 v208, v[106:109]
	s_waitcnt vmcnt(7)
	ds_write_b128 v186, v[114:117]
	s_waitcnt vmcnt(6)
	ds_write_b128 v187, v[98:101] offset:25600
	s_waitcnt vmcnt(5)
	ds_write_b128 v187, v[110:113] offset:34816
	s_branch .Latt3_wld_23

.Latt3_exit:
	s_barrier
	ds_read_b32 v188, v217
	ds_read_b32 v189, v217 offset:256
	ds_read_b32 v190, v217 offset:512
	ds_read_b32 v191, v217 offset:768
	ds_read_b32 v192, v217 offset:1024
	ds_read_b32 v193, v217 offset:1280
	ds_read_b32 v194, v217 offset:1536
	ds_read_b32 v196, v217 offset:1792
	ds_read_b32 v197, v217 offset:2048
	ds_read_b32 v198, v217 offset:2304
	ds_read_b32 v199, v217 offset:2560
	ds_read_b32 v200, v217 offset:2816
	ds_read_b32 v202, v217 offset:3072
	ds_read_b32 v203, v217 offset:3328
	s_waitcnt lgkmcnt(0)
	s_branch .LBB0_40
